# P9 unit boundary: same hoist scheme as P8 (role A's next-unit first L slot ahead of the epilogue, role B's last end-of-C barrier deferred)
# speedup vs baseline: 1.0027x; 1.0027x over previous
;     __host__ __device__ bool next(int i, Unit& u) const { const int L = i * G + c; if (L >= n) return false; u.pm = L; u.pn = L >> 2; return true; }
; #define PG8_STAGE(bufoff, gbase, voff) do { _Pragma("unroll") for (int _i = 0; _i < 2; ++_i) \
;         __builtin_amdgcn_global_load_lds((const unsigned*)((const char*)(gbase) + (voff)[_i]), (PG8_LAS unsigned*)(lds + (bufoff) + ldsw + _i * 8192), 16, 0, 0); } while (0)
; #define PG8_LDA(dst, b, h) do { _Pragma("unroll") for (int m = 0; m < 4; ++m) _Pragma("unroll") for (int k = 0; k < 2; ++k) dst[m][k] = *(const PG8_LAS bf16x8*)(lds + PG8_SA(b, h) + aoff + m * 2048 + k * 1024); } while (0)
; #define PG8_LDB(dst, b, h) do { _Pragma("unroll") for (int n = 0; n < 2; ++n) _Pragma("unroll") for (int k = 0; k < 2; ++k) dst[n][k] = *(const PG8_LAS bf16x8*)(lds + PG8_SB(b, h) + boff + n * 2048 + k * 1024); } while (0)
; #define PG8_WAIT_V(n) asm volatile("s_waitcnt vmcnt(" #n ")" ::: "memory")
; #define PG8_WAIT_L(n) asm volatile("s_waitcnt lgkmcnt(" #n ")" ::: "memory")
; #define PG8_BAR __builtin_amdgcn_s_barrier()
; #define PG8_SCHED __builtin_amdgcn_sched_barrier(0)
; template <class Epi, class Sched, bool ALIGN_EPI>
; __device__ __forceinline__ void gemm_phase(PG8_LAS unsigned char* lds, const Gemm g, const Sched& S, const Epi& E) {
;     ...
;         const bool has_next = S.next(ui + 1, nxt);
;         const size_t tail_ = has_next ? 0 : tailoff; const char* nA = (has_next ? (const char*)g.A + (size_t)nxt.pm * tstepA : cA) + (has_next ? 0 : tailoffA); const char* nB = (has_next ? (const char*)g.Bt + (size_t)nxt.pn * tstepB : cB) + tail_;
;         for (int t = 0; t < nt; t += 2) {
;             if constexpr (Epi::MIDK) { if (t == (nt >> 1)) E.midk(acc, cur, wr, fr); }
;             const bool last = (t == nt - 2);
;             const char* a1 = cA + (size_t)(t + 1) * kstepA;
;             const char* a2 = last ? nA : cA + (size_t)(t + 2) * kstepA; const char* b2 = last ? nB : cB + (size_t)(t + 2) * kstep;
;             const char* a3 = a2 + kstepA; const char* b3 = b2 + kstep;
;             PG8_LDB(B0, 0, 0); PG8_LDB(B1, 0, 1); PG8_SCHED; PG8_LDA(At, 0, 0); PG8_STAGE(PG8_SA(1, 1), a1 + hstepA, voffA);
;             PG8_WAIT_V(8); PG8_WAIT_L(0); PG8_BAR; PG8_MMA(0, 0, At, B0); PG8_MMA(0, 1, At, B1); PG8_BAR; PG8_SCHED;
.LBB0_947:
	s_add_u32 s6, s6, s30
	s_addc_u32 s7, s7, s31
	s_add_u32 s24, s34, s24
	s_addc_u32 s25, s35, s25
	s_add_u32 s57, s28, 0x100
	s_addc_u32 s58, s29, 0
	s_mov_b32 s59, -2
	s_and_b32 s60, s37, 0xfff
	s_mov_b32 s57, 0
	s_cmp_lt_u32 s37, 0x1000
	s_cbranch_scc0 .Lp9k_B_init
	s_setprio 0
	s_mov_b64 s[58:59], s[24:25]
	s_cmp_eq_u32 s42, 1
	s_cbranch_scc1 .Lp9k_A_first
	s_add_u32 s28, s28, 0x100
	s_addc_u32 s29, s29, 0
	ds_read_b128 v[158:161], v155 offset:0
	ds_read_b128 v[162:165], v155 offset:1024
	ds_read_b128 v[142:145], v157 offset:23552
	s_branch .Lp9k_A_entry
.Lp9k_A_first:
	s_add_u32 s28, s28, 0x80
	s_addc_u32 s29, s29, 0
	ds_read_b128 v[194:197], v157 offset:0
	ds_read_b128 v[198:201], v157 offset:1024
	ds_read_b128 v[202:205], v157 offset:2048
	s_add_i32 m0, s60, 0x18000
	s_nop 0
	global_load_lds_dwordx4 v132, s[28:29]
	ds_read_b128 v[206:209], v157 offset:3072
	ds_read_b128 v[210:213], v157 offset:4096
	ds_read_b128 v[214:217], v157 offset:5120
	s_add_i32 m0, s60, 0x1a000
	s_nop 0
	global_load_lds_dwordx4 v136, s[28:29]
	ds_read_b128 v[218:221], v157 offset:6144
	ds_read_b128 v[222:225], v157 offset:7168
	ds_read_b128 v[158:161], v155 offset:0
	s_add_u32 s30, s28, 0x58000
	s_addc_u32 s31, s29, 0
	s_add_i32 m0, s60, 0x19000
	s_nop 0
	global_load_lds_dwordx4 v132, s[30:31]
	ds_read_b128 v[162:165], v155 offset:1024
	ds_read_b128 v[166:169], v155 offset:2048
	ds_read_b128 v[174:177], v155 offset:3072
	s_add_i32 m0, s60, 0x1b000
	s_nop 0
	global_load_lds_dwordx4 v136, s[30:31]
	ds_read_b128 v[178:181], v155 offset:16384
	ds_read_b128 v[182:185], v155 offset:17408
	ds_read_b128 v[186:189], v155 offset:18432
	s_add_u32 s30, s28, 0x160000
	s_addc_u32 s31, s29, 0
	s_add_i32 m0, s60, 0x1c000
	s_nop 0
	global_load_lds_dwordx4 v132, s[30:31]
	ds_read_b128 v[190:193], v155 offset:19456
	ds_read_b128 v[226:229], v157 offset:16384
	ds_read_b128 v[230:233], v157 offset:17408
	s_add_i32 m0, s60, 0x1e000
	s_nop 0
	global_load_lds_dwordx4 v136, s[30:31]
	ds_read_b128 v[234:237], v157 offset:18432
	ds_read_b128 v[238:241], v157 offset:19456
	ds_read_b128 v[242:245], v157 offset:20480
	s_add_u32 s30, s28, 0x1b8000
	s_addc_u32 s31, s29, 0
	s_add_i32 m0, s60, 0x1d000
	s_nop 0
	global_load_lds_dwordx4 v132, s[30:31]
	ds_read_b128 v[246:249], v157 offset:21504
	ds_read_b128 v[250:253], v157 offset:22528
	ds_read_b128 v[142:145], v157 offset:23552
	s_add_i32 m0, s60, 0x1f000
	s_nop 0
	global_load_lds_dwordx4 v136, s[30:31]
	s_add_u32 s28, s28, 0x80
	s_addc_u32 s29, s29, 0
.Lp9k_A_entry:
	s_waitcnt vmcnt(8) lgkmcnt(0)
	s_barrier
	v_mfma_f32_16x16x32_bf16 v[126:129], v[158:161], v[194:197], 0
	v_mfma_f32_16x16x32_bf16 v[126:129], v[162:165], v[198:201], v[126:129]
	v_mfma_f32_16x16x32_bf16 v[122:125], v[174:177], v[198:201], 0
	v_mfma_f32_16x16x32_bf16 v[122:125], v[166:169], v[194:197], v[122:125]
	v_mfma_f32_16x16x32_bf16 v[114:117], v[178:181], v[194:197], 0
	v_mfma_f32_16x16x32_bf16 v[114:117], v[182:185], v[198:201], v[114:117]
	v_mfma_f32_16x16x32_bf16 v[106:109], v[190:193], v[198:201], 0
	v_mfma_f32_16x16x32_bf16 v[106:109], v[186:189], v[194:197], v[106:109]
	v_mfma_f32_16x16x32_bf16 v[90:93], v[186:189], v[202:205], 0
	v_mfma_f32_16x16x32_bf16 v[90:93], v[190:193], v[206:209], v[90:93]
	v_mfma_f32_16x16x32_bf16 v[98:101], v[182:185], v[206:209], 0
	v_mfma_f32_16x16x32_bf16 v[98:101], v[178:181], v[202:205], v[98:101]
	v_mfma_f32_16x16x32_bf16 v[110:113], v[166:169], v[202:205], 0
	v_mfma_f32_16x16x32_bf16 v[110:113], v[174:177], v[206:209], v[110:113]
	v_mfma_f32_16x16x32_bf16 v[118:121], v[162:165], v[206:209], 0
	v_mfma_f32_16x16x32_bf16 v[118:121], v[158:161], v[202:205], v[118:121]
	v_mfma_f32_16x16x32_bf16 v[102:105], v[158:161], v[210:213], 0
	v_mfma_f32_16x16x32_bf16 v[102:105], v[162:165], v[214:217], v[102:105]
	v_mfma_f32_16x16x32_bf16 v[94:97], v[174:177], v[214:217], 0
	v_mfma_f32_16x16x32_bf16 v[94:97], v[166:169], v[210:213], v[94:97]
	v_mfma_f32_16x16x32_bf16 v[82:85], v[178:181], v[210:213], 0
	v_mfma_f32_16x16x32_bf16 v[82:85], v[182:185], v[214:217], v[82:85]
	v_mfma_f32_16x16x32_bf16 v[74:77], v[190:193], v[214:217], 0
	v_mfma_f32_16x16x32_bf16 v[74:77], v[186:189], v[210:213], v[74:77]
	v_mfma_f32_16x16x32_bf16 v[66:69], v[186:189], v[218:221], 0
	v_mfma_f32_16x16x32_bf16 v[66:69], v[190:193], v[222:225], v[66:69]
	v_mfma_f32_16x16x32_bf16 v[70:73], v[182:185], v[222:225], 0
	v_mfma_f32_16x16x32_bf16 v[70:73], v[178:181], v[218:221], v[70:73]
	v_mfma_f32_16x16x32_bf16 v[78:81], v[166:169], v[218:221], 0
	v_mfma_f32_16x16x32_bf16 v[78:81], v[174:177], v[222:225], v[78:81]
	v_mfma_f32_16x16x32_bf16 v[86:89], v[162:165], v[222:225], 0
	v_mfma_f32_16x16x32_bf16 v[86:89], v[158:161], v[218:221], v[86:89]
	v_mfma_f32_16x16x32_bf16 v[62:65], v[158:161], v[226:229], 0
	v_mfma_f32_16x16x32_bf16 v[62:65], v[162:165], v[230:233], v[62:65]
	v_mfma_f32_16x16x32_bf16 v[58:61], v[174:177], v[230:233], 0
	v_mfma_f32_16x16x32_bf16 v[58:61], v[166:169], v[226:229], v[58:61]
	v_mfma_f32_16x16x32_bf16 v[50:53], v[178:181], v[226:229], 0
	v_mfma_f32_16x16x32_bf16 v[50:53], v[182:185], v[230:233], v[50:53]
	v_mfma_f32_16x16x32_bf16 v[42:45], v[190:193], v[230:233], 0
	v_mfma_f32_16x16x32_bf16 v[42:45], v[186:189], v[226:229], v[42:45]
	v_mfma_f32_16x16x32_bf16 v[26:29], v[186:189], v[234:237], 0
	v_mfma_f32_16x16x32_bf16 v[26:29], v[190:193], v[238:241], v[26:29]
	v_mfma_f32_16x16x32_bf16 v[34:37], v[182:185], v[238:241], 0
	v_mfma_f32_16x16x32_bf16 v[34:37], v[178:181], v[234:237], v[34:37]
	v_mfma_f32_16x16x32_bf16 v[46:49], v[166:169], v[234:237], 0
	v_mfma_f32_16x16x32_bf16 v[46:49], v[174:177], v[238:241], v[46:49]
	v_mfma_f32_16x16x32_bf16 v[54:57], v[162:165], v[238:241], 0
	v_mfma_f32_16x16x32_bf16 v[54:57], v[158:161], v[234:237], v[54:57]
	v_mfma_f32_16x16x32_bf16 v[38:41], v[158:161], v[242:245], 0
	v_mfma_f32_16x16x32_bf16 v[38:41], v[162:165], v[246:249], v[38:41]
	v_mfma_f32_16x16x32_bf16 v[30:33], v[174:177], v[246:249], 0
	v_mfma_f32_16x16x32_bf16 v[30:33], v[166:169], v[242:245], v[30:33]
	v_mfma_f32_16x16x32_bf16 v[18:21], v[178:181], v[242:245], 0
	v_mfma_f32_16x16x32_bf16 v[18:21], v[182:185], v[246:249], v[18:21]
	v_mfma_f32_16x16x32_bf16 v[10:13], v[190:193], v[246:249], 0
	v_mfma_f32_16x16x32_bf16 v[10:13], v[186:189], v[242:245], v[10:13]
	v_mfma_f32_16x16x32_bf16 v[2:5], v[186:189], v[250:253], 0
	v_mfma_f32_16x16x32_bf16 v[2:5], v[190:193], v[142:145], v[2:5]
	v_mfma_f32_16x16x32_bf16 v[6:9], v[182:185], v[142:145], 0
	v_mfma_f32_16x16x32_bf16 v[6:9], v[178:181], v[250:253], v[6:9]
	v_mfma_f32_16x16x32_bf16 v[14:17], v[166:169], v[250:253], 0
	v_mfma_f32_16x16x32_bf16 v[14:17], v[174:177], v[142:145], v[14:17]
	v_mfma_f32_16x16x32_bf16 v[22:25], v[162:165], v[142:145], 0
	v_mfma_f32_16x16x32_bf16 v[22:25], v[158:161], v[250:253], v[22:25]
	s_waitcnt vmcnt(0)
	s_barrier
; #define PG8_STAGE(bufoff, gbase, voff) do { _Pragma("unroll") for (int _i = 0; _i < 2; ++_i) \
;         __builtin_amdgcn_global_load_lds((const unsigned*)((const char*)(gbase) + (voff)[_i]), (PG8_LAS unsigned*)(lds + (bufoff) + ldsw + _i * 8192), 16, 0, 0); } while (0)
; #define PG8_LDA(dst, b, h) do { _Pragma("unroll") for (int m = 0; m < 4; ++m) _Pragma("unroll") for (int k = 0; k < 2; ++k) dst[m][k] = *(const PG8_LAS bf16x8*)(lds + PG8_SA(b, h) + aoff + m * 2048 + k * 1024); } while (0)
; #define PG8_LDB(dst, b, h) do { _Pragma("unroll") for (int n = 0; n < 2; ++n) _Pragma("unroll") for (int k = 0; k < 2; ++k) dst[n][k] = *(const PG8_LAS bf16x8*)(lds + PG8_SB(b, h) + boff + n * 2048 + k * 1024); } while (0)
; template <class Epi, class Sched, bool ALIGN_EPI>
; __device__ __forceinline__ void gemm_phase(PG8_LAS unsigned char* lds, const Gemm g, const Sched& S, const Epi& E) {
;     ...
;         for (int t = 0; t < nt; t += 2) {
;             if constexpr (Epi::MIDK) { if (t == (nt >> 1)) E.midk(acc, cur, wr, fr); }
;             const bool last = (t == nt - 2);
;             const char* a1 = cA + (size_t)(t + 1) * kstepA;
;             const char* a2 = last ? nA : cA + (size_t)(t + 2) * kstepA; const char* b2 = last ? nB : cB + (size_t)(t + 2) * kstep;
;             const char* a3 = a2 + kstepA; const char* b3 = b2 + kstep;
;             PG8_LDB(B0, 0, 0); PG8_LDB(B1, 0, 1); PG8_SCHED; PG8_LDA(At, 0, 0); PG8_STAGE(PG8_SA(1, 1), a1 + hstepA, voffA);
;             PG8_WAIT_V(8); PG8_WAIT_L(0); PG8_BAR; PG8_MMA(0, 0, At, B0); PG8_MMA(0, 1, At, B1); PG8_BAR; PG8_SCHED;
;             PG8_LDA(At, 0, 1); PG8_STAGE(PG8_SB(0, 0), b2, voffB); PG8_STAGE(PG8_SB(0, 1), b2 + hstepB, voffB); PG8_STAGE(PG8_SA(0, 0), a2, voffA);
;             PG8_WAIT_V(8); PG8_WAIT_L(0); PG8_BAR; PG8_MMA(1, 0, At, B0); PG8_MMA(1, 1, At, B1); PG8_BAR; PG8_SCHED;
;             PG8_LDB(B0, 1, 0); PG8_LDB(B1, 1, 1); PG8_SCHED; PG8_LDA(At, 1, 0); PG8_STAGE(PG8_SA(0, 1), a2 + hstepA, voffA);
;             PG8_WAIT_V(8); PG8_WAIT_L(0); PG8_BAR; PG8_MMA(0, 0, At, B0); PG8_MMA(0, 1, At, B1); PG8_BAR; PG8_SCHED;
;             PG8_LDA(At, 1, 1); PG8_STAGE(PG8_SB(1, 0), b3, voffB); PG8_STAGE(PG8_SB(1, 1), b3 + hstepB, voffB); PG8_STAGE(PG8_SA(1, 0), a3, voffA);
;             PG8_WAIT_V(8); PG8_WAIT_L(0); PG8_BAR; PG8_MMA(1, 0, At, B0); PG8_MMA(1, 1, At, B1); PG8_BAR; PG8_SCHED;
;         }
	ds_read_b128 v[194:197], v157 offset:32768
	ds_read_b128 v[198:201], v157 offset:33792
	ds_read_b128 v[202:205], v157 offset:34816
	s_cmp_eq_u32 s57, 43
	s_cselect_b32 s28, s58, s28
	s_cselect_b32 s29, s59, s29
	s_add_i32 m0, s60, 0x10000
	s_nop 0
	global_load_lds_dwordx4 v132, s[28:29]
	ds_read_b128 v[206:209], v157 offset:35840
	ds_read_b128 v[210:213], v157 offset:36864
	ds_read_b128 v[214:217], v157 offset:37888
	s_add_i32 m0, s60, 0x12000
	s_nop 0
	global_load_lds_dwordx4 v136, s[28:29]
	ds_read_b128 v[218:221], v157 offset:38912
	ds_read_b128 v[222:225], v157 offset:39936
	ds_read_b128 v[158:161], v155 offset:32768
	s_add_u32 s30, s28, 0x58000
	s_addc_u32 s31, s29, 0
	s_add_i32 m0, s60, 0x11000
	s_nop 0
	global_load_lds_dwordx4 v132, s[30:31]
	ds_read_b128 v[162:165], v155 offset:33792
	ds_read_b128 v[166:169], v155 offset:34816
	ds_read_b128 v[174:177], v155 offset:35840
	s_add_i32 m0, s60, 0x13000
	s_nop 0
	global_load_lds_dwordx4 v136, s[30:31]
	ds_read_b128 v[178:181], v155 offset:49152
	ds_read_b128 v[182:185], v155 offset:50176
	ds_read_b128 v[186:189], v155 offset:51200
	s_add_u32 s30, s28, 0x160000
	s_addc_u32 s31, s29, 0
	s_add_i32 m0, s60, 0x14000
	s_nop 0
	global_load_lds_dwordx4 v132, s[30:31]
	ds_read_b128 v[190:193], v155 offset:52224
	ds_read_b128 v[226:229], v157 offset:49152
	ds_read_b128 v[230:233], v157 offset:50176
	s_add_i32 m0, s60, 0x16000
	s_nop 0
	global_load_lds_dwordx4 v136, s[30:31]
	ds_read_b128 v[234:237], v157 offset:51200
	ds_read_b128 v[238:241], v157 offset:52224
	ds_read_b128 v[242:245], v157 offset:53248
	s_add_u32 s30, s28, 0x1b8000
	s_addc_u32 s31, s29, 0
	s_add_i32 m0, s60, 0x15000
	s_nop 0
	global_load_lds_dwordx4 v132, s[30:31]
	ds_read_b128 v[246:249], v157 offset:54272
	ds_read_b128 v[250:253], v157 offset:55296
	ds_read_b128 v[142:145], v157 offset:56320
	s_add_i32 m0, s60, 0x17000
	s_nop 0
	global_load_lds_dwordx4 v136, s[30:31]
	s_add_u32 s28, s28, 0x80
	s_addc_u32 s29, s29, 0
	s_waitcnt vmcnt(8) lgkmcnt(0)
	s_barrier
	v_mfma_f32_16x16x32_bf16 v[126:129], v[158:161], v[194:197], v[126:129]
	v_mfma_f32_16x16x32_bf16 v[126:129], v[162:165], v[198:201], v[126:129]
	v_mfma_f32_16x16x32_bf16 v[122:125], v[174:177], v[198:201], v[122:125]
	v_mfma_f32_16x16x32_bf16 v[122:125], v[166:169], v[194:197], v[122:125]
	v_mfma_f32_16x16x32_bf16 v[114:117], v[178:181], v[194:197], v[114:117]
	v_mfma_f32_16x16x32_bf16 v[114:117], v[182:185], v[198:201], v[114:117]
	v_mfma_f32_16x16x32_bf16 v[106:109], v[190:193], v[198:201], v[106:109]
	v_mfma_f32_16x16x32_bf16 v[106:109], v[186:189], v[194:197], v[106:109]
	v_mfma_f32_16x16x32_bf16 v[90:93], v[186:189], v[202:205], v[90:93]
	v_mfma_f32_16x16x32_bf16 v[90:93], v[190:193], v[206:209], v[90:93]
	v_mfma_f32_16x16x32_bf16 v[98:101], v[182:185], v[206:209], v[98:101]
	v_mfma_f32_16x16x32_bf16 v[98:101], v[178:181], v[202:205], v[98:101]
	v_mfma_f32_16x16x32_bf16 v[110:113], v[166:169], v[202:205], v[110:113]
	v_mfma_f32_16x16x32_bf16 v[110:113], v[174:177], v[206:209], v[110:113]
	v_mfma_f32_16x16x32_bf16 v[118:121], v[162:165], v[206:209], v[118:121]
	v_mfma_f32_16x16x32_bf16 v[118:121], v[158:161], v[202:205], v[118:121]
	v_mfma_f32_16x16x32_bf16 v[102:105], v[158:161], v[210:213], v[102:105]
	v_mfma_f32_16x16x32_bf16 v[102:105], v[162:165], v[214:217], v[102:105]
	v_mfma_f32_16x16x32_bf16 v[94:97], v[174:177], v[214:217], v[94:97]
	v_mfma_f32_16x16x32_bf16 v[94:97], v[166:169], v[210:213], v[94:97]
	v_mfma_f32_16x16x32_bf16 v[82:85], v[178:181], v[210:213], v[82:85]
	v_mfma_f32_16x16x32_bf16 v[82:85], v[182:185], v[214:217], v[82:85]
	v_mfma_f32_16x16x32_bf16 v[74:77], v[190:193], v[214:217], v[74:77]
	v_mfma_f32_16x16x32_bf16 v[74:77], v[186:189], v[210:213], v[74:77]
	v_mfma_f32_16x16x32_bf16 v[66:69], v[186:189], v[218:221], v[66:69]
	v_mfma_f32_16x16x32_bf16 v[66:69], v[190:193], v[222:225], v[66:69]
	v_mfma_f32_16x16x32_bf16 v[70:73], v[182:185], v[222:225], v[70:73]
	v_mfma_f32_16x16x32_bf16 v[70:73], v[178:181], v[218:221], v[70:73]
	v_mfma_f32_16x16x32_bf16 v[78:81], v[166:169], v[218:221], v[78:81]
	v_mfma_f32_16x16x32_bf16 v[78:81], v[174:177], v[222:225], v[78:81]
	v_mfma_f32_16x16x32_bf16 v[86:89], v[162:165], v[222:225], v[86:89]
	v_mfma_f32_16x16x32_bf16 v[86:89], v[158:161], v[218:221], v[86:89]
	v_mfma_f32_16x16x32_bf16 v[62:65], v[158:161], v[226:229], v[62:65]
	v_mfma_f32_16x16x32_bf16 v[62:65], v[162:165], v[230:233], v[62:65]
	v_mfma_f32_16x16x32_bf16 v[58:61], v[174:177], v[230:233], v[58:61]
	v_mfma_f32_16x16x32_bf16 v[58:61], v[166:169], v[226:229], v[58:61]
	v_mfma_f32_16x16x32_bf16 v[50:53], v[178:181], v[226:229], v[50:53]
	v_mfma_f32_16x16x32_bf16 v[50:53], v[182:185], v[230:233], v[50:53]
	v_mfma_f32_16x16x32_bf16 v[42:45], v[190:193], v[230:233], v[42:45]
	v_mfma_f32_16x16x32_bf16 v[42:45], v[186:189], v[226:229], v[42:45]
	v_mfma_f32_16x16x32_bf16 v[26:29], v[186:189], v[234:237], v[26:29]
	v_mfma_f32_16x16x32_bf16 v[26:29], v[190:193], v[238:241], v[26:29]
	v_mfma_f32_16x16x32_bf16 v[34:37], v[182:185], v[238:241], v[34:37]
	v_mfma_f32_16x16x32_bf16 v[34:37], v[178:181], v[234:237], v[34:37]
	v_mfma_f32_16x16x32_bf16 v[46:49], v[166:169], v[234:237], v[46:49]
	v_mfma_f32_16x16x32_bf16 v[46:49], v[174:177], v[238:241], v[46:49]
	v_mfma_f32_16x16x32_bf16 v[54:57], v[162:165], v[238:241], v[54:57]
	v_mfma_f32_16x16x32_bf16 v[54:57], v[158:161], v[234:237], v[54:57]
	v_mfma_f32_16x16x32_bf16 v[38:41], v[158:161], v[242:245], v[38:41]
	v_mfma_f32_16x16x32_bf16 v[38:41], v[162:165], v[246:249], v[38:41]
	v_mfma_f32_16x16x32_bf16 v[30:33], v[174:177], v[246:249], v[30:33]
	v_mfma_f32_16x16x32_bf16 v[30:33], v[166:169], v[242:245], v[30:33]
	v_mfma_f32_16x16x32_bf16 v[18:21], v[178:181], v[242:245], v[18:21]
	v_mfma_f32_16x16x32_bf16 v[18:21], v[182:185], v[246:249], v[18:21]
	v_mfma_f32_16x16x32_bf16 v[10:13], v[190:193], v[246:249], v[10:13]
	v_mfma_f32_16x16x32_bf16 v[10:13], v[186:189], v[242:245], v[10:13]
	v_mfma_f32_16x16x32_bf16 v[2:5], v[186:189], v[250:253], v[2:5]
	v_mfma_f32_16x16x32_bf16 v[2:5], v[190:193], v[142:145], v[2:5]
	v_mfma_f32_16x16x32_bf16 v[6:9], v[182:185], v[142:145], v[6:9]
	v_mfma_f32_16x16x32_bf16 v[6:9], v[178:181], v[250:253], v[6:9]
	v_mfma_f32_16x16x32_bf16 v[14:17], v[166:169], v[250:253], v[14:17]
	v_mfma_f32_16x16x32_bf16 v[14:17], v[174:177], v[142:145], v[14:17]
	v_mfma_f32_16x16x32_bf16 v[22:25], v[162:165], v[142:145], v[22:25]
	v_mfma_f32_16x16x32_bf16 v[22:25], v[158:161], v[250:253], v[22:25]
	s_waitcnt vmcnt(0)
	s_barrier
	s_add_i32 s57, s57, 1
; #define PG8_STAGE(bufoff, gbase, voff) do { _Pragma("unroll") for (int _i = 0; _i < 2; ++_i) \
;         __builtin_amdgcn_global_load_lds((const unsigned*)((const char*)(gbase) + (voff)[_i]), (PG8_LAS unsigned*)(lds + (bufoff) + ldsw + _i * 8192), 16, 0, 0); } while (0)
; #define PG8_LDA(dst, b, h) do { _Pragma("unroll") for (int m = 0; m < 4; ++m) _Pragma("unroll") for (int k = 0; k < 2; ++k) dst[m][k] = *(const PG8_LAS bf16x8*)(lds + PG8_SA(b, h) + aoff + m * 2048 + k * 1024); } while (0)
; #define PG8_LDB(dst, b, h) do { _Pragma("unroll") for (int n = 0; n < 2; ++n) _Pragma("unroll") for (int k = 0; k < 2; ++k) dst[n][k] = *(const PG8_LAS bf16x8*)(lds + PG8_SB(b, h) + boff + n * 2048 + k * 1024); } while (0)
; template <class Epi, class Sched, bool ALIGN_EPI>
; __device__ __forceinline__ void gemm_phase(PG8_LAS unsigned char* lds, const Gemm g, const Sched& S, const Epi& E) {
;     ...
;         for (int t = 0; t < nt; t += 2) {
;             if constexpr (Epi::MIDK) { if (t == (nt >> 1)) E.midk(acc, cur, wr, fr); }
;             const bool last = (t == nt - 2);
;             const char* a1 = cA + (size_t)(t + 1) * kstepA;
;             const char* a2 = last ? nA : cA + (size_t)(t + 2) * kstepA; const char* b2 = last ? nB : cB + (size_t)(t + 2) * kstep;
;             const char* a3 = a2 + kstepA; const char* b3 = b2 + kstep;
;             PG8_LDB(B0, 0, 0); PG8_LDB(B1, 0, 1); PG8_SCHED; PG8_LDA(At, 0, 0); PG8_STAGE(PG8_SA(1, 1), a1 + hstepA, voffA);
;             PG8_WAIT_V(8); PG8_WAIT_L(0); PG8_BAR; PG8_MMA(0, 0, At, B0); PG8_MMA(0, 1, At, B1); PG8_BAR; PG8_SCHED;
;             PG8_LDA(At, 0, 1); PG8_STAGE(PG8_SB(0, 0), b2, voffB); PG8_STAGE(PG8_SB(0, 1), b2 + hstepB, voffB); PG8_STAGE(PG8_SA(0, 0), a2, voffA);
;             PG8_WAIT_V(8); PG8_WAIT_L(0); PG8_BAR; PG8_MMA(1, 0, At, B0); PG8_MMA(1, 1, At, B1); PG8_BAR; PG8_SCHED;
;             PG8_LDB(B0, 1, 0); PG8_LDB(B1, 1, 1); PG8_SCHED; PG8_LDA(At, 1, 0); PG8_STAGE(PG8_SA(0, 1), a2 + hstepA, voffA);
;             PG8_WAIT_V(8); PG8_WAIT_L(0); PG8_BAR; PG8_MMA(0, 0, At, B0); PG8_MMA(0, 1, At, B1); PG8_BAR; PG8_SCHED;
;             PG8_LDA(At, 1, 1); PG8_STAGE(PG8_SB(1, 0), b3, voffB); PG8_STAGE(PG8_SB(1, 1), b3 + hstepB, voffB); PG8_STAGE(PG8_SA(1, 0), a3, voffA);
;             PG8_WAIT_V(8); PG8_WAIT_L(0); PG8_BAR; PG8_MMA(1, 0, At, B0); PG8_MMA(1, 1, At, B1); PG8_BAR; PG8_SCHED;
;         }
.Lp9k_A_loop:
	ds_read_b128 v[194:197], v157 offset:0
	ds_read_b128 v[198:201], v157 offset:1024
	ds_read_b128 v[202:205], v157 offset:2048
	s_add_i32 m0, s60, 0x18000
	s_nop 0
	global_load_lds_dwordx4 v132, s[28:29]
	ds_read_b128 v[206:209], v157 offset:3072
	ds_read_b128 v[210:213], v157 offset:4096
	ds_read_b128 v[214:217], v157 offset:5120
	s_add_i32 m0, s60, 0x1a000
	s_nop 0
	global_load_lds_dwordx4 v136, s[28:29]
	ds_read_b128 v[218:221], v157 offset:6144
	ds_read_b128 v[222:225], v157 offset:7168
	ds_read_b128 v[158:161], v155 offset:0
	s_add_u32 s30, s28, 0x58000
	s_addc_u32 s31, s29, 0
	s_add_i32 m0, s60, 0x19000
	s_nop 0
	global_load_lds_dwordx4 v132, s[30:31]
	ds_read_b128 v[162:165], v155 offset:1024
	ds_read_b128 v[166:169], v155 offset:2048
	ds_read_b128 v[174:177], v155 offset:3072
	s_add_i32 m0, s60, 0x1b000
	s_nop 0
	global_load_lds_dwordx4 v136, s[30:31]
	ds_read_b128 v[178:181], v155 offset:16384
	ds_read_b128 v[182:185], v155 offset:17408
	ds_read_b128 v[186:189], v155 offset:18432
	s_add_u32 s30, s28, 0x160000
	s_addc_u32 s31, s29, 0
	s_add_i32 m0, s60, 0x1c000
	s_nop 0
	global_load_lds_dwordx4 v132, s[30:31]
	ds_read_b128 v[190:193], v155 offset:19456
	ds_read_b128 v[226:229], v157 offset:16384
	ds_read_b128 v[230:233], v157 offset:17408
	s_add_i32 m0, s60, 0x1e000
	s_nop 0
	global_load_lds_dwordx4 v136, s[30:31]
	ds_read_b128 v[234:237], v157 offset:18432
	ds_read_b128 v[238:241], v157 offset:19456
	ds_read_b128 v[242:245], v157 offset:20480
	s_add_u32 s30, s28, 0x1b8000
	s_addc_u32 s31, s29, 0
	s_add_i32 m0, s60, 0x1d000
	s_nop 0
	global_load_lds_dwordx4 v132, s[30:31]
	ds_read_b128 v[246:249], v157 offset:21504
	ds_read_b128 v[250:253], v157 offset:22528
	ds_read_b128 v[142:145], v157 offset:23552
	s_add_i32 m0, s60, 0x1f000
	s_nop 0
	global_load_lds_dwordx4 v136, s[30:31]
	s_add_u32 s28, s28, 0x80
	s_addc_u32 s29, s29, 0
	s_waitcnt vmcnt(8) lgkmcnt(0)
	s_barrier
	v_mfma_f32_16x16x32_bf16 v[126:129], v[158:161], v[194:197], v[126:129]
	v_mfma_f32_16x16x32_bf16 v[126:129], v[162:165], v[198:201], v[126:129]
	v_mfma_f32_16x16x32_bf16 v[122:125], v[174:177], v[198:201], v[122:125]
	v_mfma_f32_16x16x32_bf16 v[122:125], v[166:169], v[194:197], v[122:125]
	v_mfma_f32_16x16x32_bf16 v[114:117], v[178:181], v[194:197], v[114:117]
	v_mfma_f32_16x16x32_bf16 v[114:117], v[182:185], v[198:201], v[114:117]
	v_mfma_f32_16x16x32_bf16 v[106:109], v[190:193], v[198:201], v[106:109]
	v_mfma_f32_16x16x32_bf16 v[106:109], v[186:189], v[194:197], v[106:109]
	v_mfma_f32_16x16x32_bf16 v[90:93], v[186:189], v[202:205], v[90:93]
	v_mfma_f32_16x16x32_bf16 v[90:93], v[190:193], v[206:209], v[90:93]
	v_mfma_f32_16x16x32_bf16 v[98:101], v[182:185], v[206:209], v[98:101]
	v_mfma_f32_16x16x32_bf16 v[98:101], v[178:181], v[202:205], v[98:101]
	v_mfma_f32_16x16x32_bf16 v[110:113], v[166:169], v[202:205], v[110:113]
	v_mfma_f32_16x16x32_bf16 v[110:113], v[174:177], v[206:209], v[110:113]
	v_mfma_f32_16x16x32_bf16 v[118:121], v[162:165], v[206:209], v[118:121]
	v_mfma_f32_16x16x32_bf16 v[118:121], v[158:161], v[202:205], v[118:121]
	v_mfma_f32_16x16x32_bf16 v[102:105], v[158:161], v[210:213], v[102:105]
	v_mfma_f32_16x16x32_bf16 v[102:105], v[162:165], v[214:217], v[102:105]
	v_mfma_f32_16x16x32_bf16 v[94:97], v[174:177], v[214:217], v[94:97]
	v_mfma_f32_16x16x32_bf16 v[94:97], v[166:169], v[210:213], v[94:97]
	v_mfma_f32_16x16x32_bf16 v[82:85], v[178:181], v[210:213], v[82:85]
	v_mfma_f32_16x16x32_bf16 v[82:85], v[182:185], v[214:217], v[82:85]
	v_mfma_f32_16x16x32_bf16 v[74:77], v[190:193], v[214:217], v[74:77]
	v_mfma_f32_16x16x32_bf16 v[74:77], v[186:189], v[210:213], v[74:77]
	v_mfma_f32_16x16x32_bf16 v[66:69], v[186:189], v[218:221], v[66:69]
	v_mfma_f32_16x16x32_bf16 v[66:69], v[190:193], v[222:225], v[66:69]
	v_mfma_f32_16x16x32_bf16 v[70:73], v[182:185], v[222:225], v[70:73]
	v_mfma_f32_16x16x32_bf16 v[70:73], v[178:181], v[218:221], v[70:73]
	v_mfma_f32_16x16x32_bf16 v[78:81], v[166:169], v[218:221], v[78:81]
	v_mfma_f32_16x16x32_bf16 v[78:81], v[174:177], v[222:225], v[78:81]
	v_mfma_f32_16x16x32_bf16 v[86:89], v[162:165], v[222:225], v[86:89]
	v_mfma_f32_16x16x32_bf16 v[86:89], v[158:161], v[218:221], v[86:89]
	v_mfma_f32_16x16x32_bf16 v[62:65], v[158:161], v[226:229], v[62:65]
	v_mfma_f32_16x16x32_bf16 v[62:65], v[162:165], v[230:233], v[62:65]
	v_mfma_f32_16x16x32_bf16 v[58:61], v[174:177], v[230:233], v[58:61]
	v_mfma_f32_16x16x32_bf16 v[58:61], v[166:169], v[226:229], v[58:61]
	v_mfma_f32_16x16x32_bf16 v[50:53], v[178:181], v[226:229], v[50:53]
	v_mfma_f32_16x16x32_bf16 v[50:53], v[182:185], v[230:233], v[50:53]
	v_mfma_f32_16x16x32_bf16 v[42:45], v[190:193], v[230:233], v[42:45]
	v_mfma_f32_16x16x32_bf16 v[42:45], v[186:189], v[226:229], v[42:45]
	v_mfma_f32_16x16x32_bf16 v[26:29], v[186:189], v[234:237], v[26:29]
	v_mfma_f32_16x16x32_bf16 v[26:29], v[190:193], v[238:241], v[26:29]
	v_mfma_f32_16x16x32_bf16 v[34:37], v[182:185], v[238:241], v[34:37]
	v_mfma_f32_16x16x32_bf16 v[34:37], v[178:181], v[234:237], v[34:37]
	v_mfma_f32_16x16x32_bf16 v[46:49], v[166:169], v[234:237], v[46:49]
	v_mfma_f32_16x16x32_bf16 v[46:49], v[174:177], v[238:241], v[46:49]
	v_mfma_f32_16x16x32_bf16 v[54:57], v[162:165], v[238:241], v[54:57]
	v_mfma_f32_16x16x32_bf16 v[54:57], v[158:161], v[234:237], v[54:57]
	v_mfma_f32_16x16x32_bf16 v[38:41], v[158:161], v[242:245], v[38:41]
	v_mfma_f32_16x16x32_bf16 v[38:41], v[162:165], v[246:249], v[38:41]
	v_mfma_f32_16x16x32_bf16 v[30:33], v[174:177], v[246:249], v[30:33]
	v_mfma_f32_16x16x32_bf16 v[30:33], v[166:169], v[242:245], v[30:33]
	v_mfma_f32_16x16x32_bf16 v[18:21], v[178:181], v[242:245], v[18:21]
	v_mfma_f32_16x16x32_bf16 v[18:21], v[182:185], v[246:249], v[18:21]
	v_mfma_f32_16x16x32_bf16 v[10:13], v[190:193], v[246:249], v[10:13]
	v_mfma_f32_16x16x32_bf16 v[10:13], v[186:189], v[242:245], v[10:13]
	v_mfma_f32_16x16x32_bf16 v[2:5], v[186:189], v[250:253], v[2:5]
	v_mfma_f32_16x16x32_bf16 v[2:5], v[190:193], v[142:145], v[2:5]
	v_mfma_f32_16x16x32_bf16 v[6:9], v[182:185], v[142:145], v[6:9]
	v_mfma_f32_16x16x32_bf16 v[6:9], v[178:181], v[250:253], v[6:9]
	v_mfma_f32_16x16x32_bf16 v[14:17], v[166:169], v[250:253], v[14:17]
	v_mfma_f32_16x16x32_bf16 v[14:17], v[174:177], v[142:145], v[14:17]
	v_mfma_f32_16x16x32_bf16 v[22:25], v[162:165], v[142:145], v[22:25]
	v_mfma_f32_16x16x32_bf16 v[22:25], v[158:161], v[250:253], v[22:25]
	s_waitcnt vmcnt(0)
	s_barrier
; #define PG8_STAGE(bufoff, gbase, voff) do { _Pragma("unroll") for (int _i = 0; _i < 2; ++_i) \
;         __builtin_amdgcn_global_load_lds((const unsigned*)((const char*)(gbase) + (voff)[_i]), (PG8_LAS unsigned*)(lds + (bufoff) + ldsw + _i * 8192), 16, 0, 0); } while (0)
; #define PG8_LDA(dst, b, h) do { _Pragma("unroll") for (int m = 0; m < 4; ++m) _Pragma("unroll") for (int k = 0; k < 2; ++k) dst[m][k] = *(const PG8_LAS bf16x8*)(lds + PG8_SA(b, h) + aoff + m * 2048 + k * 1024); } while (0)
; #define PG8_LDB(dst, b, h) do { _Pragma("unroll") for (int n = 0; n < 2; ++n) _Pragma("unroll") for (int k = 0; k < 2; ++k) dst[n][k] = *(const PG8_LAS bf16x8*)(lds + PG8_SB(b, h) + boff + n * 2048 + k * 1024); } while (0)
; template <class Epi, class Sched, bool ALIGN_EPI>
; __device__ __forceinline__ void gemm_phase(PG8_LAS unsigned char* lds, const Gemm g, const Sched& S, const Epi& E) {
;     ...
;         for (int t = 0; t < nt; t += 2) {
;             if constexpr (Epi::MIDK) { if (t == (nt >> 1)) E.midk(acc, cur, wr, fr); }
;             const bool last = (t == nt - 2);
;             const char* a1 = cA + (size_t)(t + 1) * kstepA;
;             const char* a2 = last ? nA : cA + (size_t)(t + 2) * kstepA; const char* b2 = last ? nB : cB + (size_t)(t + 2) * kstep;
;             const char* a3 = a2 + kstepA; const char* b3 = b2 + kstep;
;             PG8_LDB(B0, 0, 0); PG8_LDB(B1, 0, 1); PG8_SCHED; PG8_LDA(At, 0, 0); PG8_STAGE(PG8_SA(1, 1), a1 + hstepA, voffA);
;             PG8_WAIT_V(8); PG8_WAIT_L(0); PG8_BAR; PG8_MMA(0, 0, At, B0); PG8_MMA(0, 1, At, B1); PG8_BAR; PG8_SCHED;
;             PG8_LDA(At, 0, 1); PG8_STAGE(PG8_SB(0, 0), b2, voffB); PG8_STAGE(PG8_SB(0, 1), b2 + hstepB, voffB); PG8_STAGE(PG8_SA(0, 0), a2, voffA);
;             PG8_WAIT_V(8); PG8_WAIT_L(0); PG8_BAR; PG8_MMA(1, 0, At, B0); PG8_MMA(1, 1, At, B1); PG8_BAR; PG8_SCHED;
;             PG8_LDB(B0, 1, 0); PG8_LDB(B1, 1, 1); PG8_SCHED; PG8_LDA(At, 1, 0); PG8_STAGE(PG8_SA(0, 1), a2 + hstepA, voffA);
;             PG8_WAIT_V(8); PG8_WAIT_L(0); PG8_BAR; PG8_MMA(0, 0, At, B0); PG8_MMA(0, 1, At, B1); PG8_BAR; PG8_SCHED;
;             PG8_LDA(At, 1, 1); PG8_STAGE(PG8_SB(1, 0), b3, voffB); PG8_STAGE(PG8_SB(1, 1), b3 + hstepB, voffB); PG8_STAGE(PG8_SA(1, 0), a3, voffA);
;             PG8_WAIT_V(8); PG8_WAIT_L(0); PG8_BAR; PG8_MMA(1, 0, At, B0); PG8_MMA(1, 1, At, B1); PG8_BAR; PG8_SCHED;
;         }
	ds_read_b128 v[194:197], v157 offset:32768
	ds_read_b128 v[198:201], v157 offset:33792
	ds_read_b128 v[202:205], v157 offset:34816
	s_cmp_eq_u32 s57, 43
	s_cselect_b32 s28, s58, s28
	s_cselect_b32 s29, s59, s29
	s_add_i32 m0, s60, 0x10000
	s_nop 0
	global_load_lds_dwordx4 v132, s[28:29]
	ds_read_b128 v[206:209], v157 offset:35840
	ds_read_b128 v[210:213], v157 offset:36864
	ds_read_b128 v[214:217], v157 offset:37888
	s_add_i32 m0, s60, 0x12000
	s_nop 0
	global_load_lds_dwordx4 v136, s[28:29]
	ds_read_b128 v[218:221], v157 offset:38912
	ds_read_b128 v[222:225], v157 offset:39936
	ds_read_b128 v[158:161], v155 offset:32768
	s_add_u32 s30, s28, 0x58000
	s_addc_u32 s31, s29, 0
	s_add_i32 m0, s60, 0x11000
	s_nop 0
	global_load_lds_dwordx4 v132, s[30:31]
	ds_read_b128 v[162:165], v155 offset:33792
	ds_read_b128 v[166:169], v155 offset:34816
	ds_read_b128 v[174:177], v155 offset:35840
	s_add_i32 m0, s60, 0x13000
	s_nop 0
	global_load_lds_dwordx4 v136, s[30:31]
	ds_read_b128 v[178:181], v155 offset:49152
	ds_read_b128 v[182:185], v155 offset:50176
	ds_read_b128 v[186:189], v155 offset:51200
	s_add_u32 s30, s28, 0x160000
	s_addc_u32 s31, s29, 0
	s_add_i32 m0, s60, 0x14000
	s_nop 0
	global_load_lds_dwordx4 v132, s[30:31]
	ds_read_b128 v[190:193], v155 offset:52224
	ds_read_b128 v[226:229], v157 offset:49152
	ds_read_b128 v[230:233], v157 offset:50176
	s_add_i32 m0, s60, 0x16000
	s_nop 0
	global_load_lds_dwordx4 v136, s[30:31]
	ds_read_b128 v[234:237], v157 offset:51200
	ds_read_b128 v[238:241], v157 offset:52224
	ds_read_b128 v[242:245], v157 offset:53248
	s_add_u32 s30, s28, 0x1b8000
	s_addc_u32 s31, s29, 0
	s_add_i32 m0, s60, 0x15000
	s_nop 0
	global_load_lds_dwordx4 v132, s[30:31]
	ds_read_b128 v[246:249], v157 offset:54272
	ds_read_b128 v[250:253], v157 offset:55296
	ds_read_b128 v[142:145], v157 offset:56320
	s_add_i32 m0, s60, 0x17000
	s_nop 0
	global_load_lds_dwordx4 v136, s[30:31]
	s_add_u32 s28, s28, 0x80
	s_addc_u32 s29, s29, 0
	s_waitcnt vmcnt(8) lgkmcnt(0)
	s_barrier
	v_mfma_f32_16x16x32_bf16 v[126:129], v[158:161], v[194:197], v[126:129]
	v_mfma_f32_16x16x32_bf16 v[126:129], v[162:165], v[198:201], v[126:129]
	v_mfma_f32_16x16x32_bf16 v[122:125], v[174:177], v[198:201], v[122:125]
	v_mfma_f32_16x16x32_bf16 v[122:125], v[166:169], v[194:197], v[122:125]
	v_mfma_f32_16x16x32_bf16 v[114:117], v[178:181], v[194:197], v[114:117]
	v_mfma_f32_16x16x32_bf16 v[114:117], v[182:185], v[198:201], v[114:117]
	v_mfma_f32_16x16x32_bf16 v[106:109], v[190:193], v[198:201], v[106:109]
	v_mfma_f32_16x16x32_bf16 v[106:109], v[186:189], v[194:197], v[106:109]
	v_mfma_f32_16x16x32_bf16 v[90:93], v[186:189], v[202:205], v[90:93]
	v_mfma_f32_16x16x32_bf16 v[90:93], v[190:193], v[206:209], v[90:93]
	v_mfma_f32_16x16x32_bf16 v[98:101], v[182:185], v[206:209], v[98:101]
	v_mfma_f32_16x16x32_bf16 v[98:101], v[178:181], v[202:205], v[98:101]
	v_mfma_f32_16x16x32_bf16 v[110:113], v[166:169], v[202:205], v[110:113]
	v_mfma_f32_16x16x32_bf16 v[110:113], v[174:177], v[206:209], v[110:113]
	v_mfma_f32_16x16x32_bf16 v[118:121], v[162:165], v[206:209], v[118:121]
	v_mfma_f32_16x16x32_bf16 v[118:121], v[158:161], v[202:205], v[118:121]
	v_mfma_f32_16x16x32_bf16 v[102:105], v[158:161], v[210:213], v[102:105]
	v_mfma_f32_16x16x32_bf16 v[102:105], v[162:165], v[214:217], v[102:105]
	v_mfma_f32_16x16x32_bf16 v[94:97], v[174:177], v[214:217], v[94:97]
	v_mfma_f32_16x16x32_bf16 v[94:97], v[166:169], v[210:213], v[94:97]
	v_mfma_f32_16x16x32_bf16 v[82:85], v[178:181], v[210:213], v[82:85]
	v_mfma_f32_16x16x32_bf16 v[82:85], v[182:185], v[214:217], v[82:85]
	v_mfma_f32_16x16x32_bf16 v[74:77], v[190:193], v[214:217], v[74:77]
	v_mfma_f32_16x16x32_bf16 v[74:77], v[186:189], v[210:213], v[74:77]
	v_mfma_f32_16x16x32_bf16 v[66:69], v[186:189], v[218:221], v[66:69]
	v_mfma_f32_16x16x32_bf16 v[66:69], v[190:193], v[222:225], v[66:69]
	v_mfma_f32_16x16x32_bf16 v[70:73], v[182:185], v[222:225], v[70:73]
	v_mfma_f32_16x16x32_bf16 v[70:73], v[178:181], v[218:221], v[70:73]
	v_mfma_f32_16x16x32_bf16 v[78:81], v[166:169], v[218:221], v[78:81]
	v_mfma_f32_16x16x32_bf16 v[78:81], v[174:177], v[222:225], v[78:81]
	v_mfma_f32_16x16x32_bf16 v[86:89], v[162:165], v[222:225], v[86:89]
	v_mfma_f32_16x16x32_bf16 v[86:89], v[158:161], v[218:221], v[86:89]
	v_mfma_f32_16x16x32_bf16 v[62:65], v[158:161], v[226:229], v[62:65]
	v_mfma_f32_16x16x32_bf16 v[62:65], v[162:165], v[230:233], v[62:65]
	v_mfma_f32_16x16x32_bf16 v[58:61], v[174:177], v[230:233], v[58:61]
	v_mfma_f32_16x16x32_bf16 v[58:61], v[166:169], v[226:229], v[58:61]
	v_mfma_f32_16x16x32_bf16 v[50:53], v[178:181], v[226:229], v[50:53]
	v_mfma_f32_16x16x32_bf16 v[50:53], v[182:185], v[230:233], v[50:53]
	v_mfma_f32_16x16x32_bf16 v[42:45], v[190:193], v[230:233], v[42:45]
	v_mfma_f32_16x16x32_bf16 v[42:45], v[186:189], v[226:229], v[42:45]
	v_mfma_f32_16x16x32_bf16 v[26:29], v[186:189], v[234:237], v[26:29]
	v_mfma_f32_16x16x32_bf16 v[26:29], v[190:193], v[238:241], v[26:29]
	v_mfma_f32_16x16x32_bf16 v[34:37], v[182:185], v[238:241], v[34:37]
	v_mfma_f32_16x16x32_bf16 v[34:37], v[178:181], v[234:237], v[34:37]
	v_mfma_f32_16x16x32_bf16 v[46:49], v[166:169], v[234:237], v[46:49]
	v_mfma_f32_16x16x32_bf16 v[46:49], v[174:177], v[238:241], v[46:49]
	v_mfma_f32_16x16x32_bf16 v[54:57], v[162:165], v[238:241], v[54:57]
	v_mfma_f32_16x16x32_bf16 v[54:57], v[158:161], v[234:237], v[54:57]
	v_mfma_f32_16x16x32_bf16 v[38:41], v[158:161], v[242:245], v[38:41]
	v_mfma_f32_16x16x32_bf16 v[38:41], v[162:165], v[246:249], v[38:41]
	v_mfma_f32_16x16x32_bf16 v[30:33], v[174:177], v[246:249], v[30:33]
	v_mfma_f32_16x16x32_bf16 v[30:33], v[166:169], v[242:245], v[30:33]
	v_mfma_f32_16x16x32_bf16 v[18:21], v[178:181], v[242:245], v[18:21]
	v_mfma_f32_16x16x32_bf16 v[18:21], v[182:185], v[246:249], v[18:21]
	v_mfma_f32_16x16x32_bf16 v[10:13], v[190:193], v[246:249], v[10:13]
	v_mfma_f32_16x16x32_bf16 v[10:13], v[186:189], v[242:245], v[10:13]
	v_mfma_f32_16x16x32_bf16 v[2:5], v[186:189], v[250:253], v[2:5]
	v_mfma_f32_16x16x32_bf16 v[2:5], v[190:193], v[142:145], v[2:5]
	v_mfma_f32_16x16x32_bf16 v[6:9], v[182:185], v[142:145], v[6:9]
	v_mfma_f32_16x16x32_bf16 v[6:9], v[178:181], v[250:253], v[6:9]
	v_mfma_f32_16x16x32_bf16 v[14:17], v[166:169], v[250:253], v[14:17]
	v_mfma_f32_16x16x32_bf16 v[14:17], v[174:177], v[142:145], v[14:17]
	v_mfma_f32_16x16x32_bf16 v[22:25], v[162:165], v[142:145], v[22:25]
	v_mfma_f32_16x16x32_bf16 v[22:25], v[158:161], v[250:253], v[22:25]
	s_waitcnt vmcnt(0)
	s_barrier
; #define PG8_STAGE(bufoff, gbase, voff) do { _Pragma("unroll") for (int _i = 0; _i < 2; ++_i) \
;         __builtin_amdgcn_global_load_lds((const unsigned*)((const char*)(gbase) + (voff)[_i]), (PG8_LAS unsigned*)(lds + (bufoff) + ldsw + _i * 8192), 16, 0, 0); } while (0)
; #define PG8_LDA(dst, b, h) do { _Pragma("unroll") for (int m = 0; m < 4; ++m) _Pragma("unroll") for (int k = 0; k < 2; ++k) dst[m][k] = *(const PG8_LAS bf16x8*)(lds + PG8_SA(b, h) + aoff + m * 2048 + k * 1024); } while (0)
; #define PG8_BAR __builtin_amdgcn_s_barrier()
; template <class Epi, class Sched, bool ALIGN_EPI>
; __device__ __forceinline__ void gemm_phase(PG8_LAS unsigned char* lds, const Gemm g, const Sched& S, const Epi& E) {
;     ...
;         for (int t = 0; t < nt; t += 2) {
;             if constexpr (Epi::MIDK) { if (t == (nt >> 1)) E.midk(acc, cur, wr, fr); }
;             const bool last = (t == nt - 2);
;             const char* a1 = cA + (size_t)(t + 1) * kstepA;
;             const char* a2 = last ? nA : cA + (size_t)(t + 2) * kstepA; const char* b2 = last ? nB : cB + (size_t)(t + 2) * kstep;
;             const char* a3 = a2 + kstepA; const char* b3 = b2 + kstep;
;             PG8_LDB(B0, 0, 0); PG8_LDB(B1, 0, 1); PG8_SCHED; PG8_LDA(At, 0, 0); PG8_STAGE(PG8_SA(1, 1), a1 + hstepA, voffA);
;             PG8_WAIT_V(8); PG8_WAIT_L(0); PG8_BAR; PG8_MMA(0, 0, At, B0); PG8_MMA(0, 1, At, B1); PG8_BAR; PG8_SCHED;
;             PG8_LDA(At, 0, 1); PG8_STAGE(PG8_SB(0, 0), b2, voffB); PG8_STAGE(PG8_SB(0, 1), b2 + hstepB, voffB); PG8_STAGE(PG8_SA(0, 0), a2, voffA);
;             PG8_WAIT_V(8); PG8_WAIT_L(0); PG8_BAR; PG8_MMA(1, 0, At, B0); PG8_MMA(1, 1, At, B1); PG8_BAR; PG8_SCHED;
;             PG8_LDB(B0, 1, 0); PG8_LDB(B1, 1, 1); PG8_SCHED; PG8_LDA(At, 1, 0); PG8_STAGE(PG8_SA(0, 1), a2 + hstepA, voffA);
;             PG8_WAIT_V(8); PG8_WAIT_L(0); PG8_BAR; PG8_MMA(0, 0, At, B0); PG8_MMA(0, 1, At, B1); PG8_BAR; PG8_SCHED;
;             PG8_LDA(At, 1, 1); PG8_STAGE(PG8_SB(1, 0), b3, voffB); PG8_STAGE(PG8_SB(1, 1), b3 + hstepB, voffB); PG8_STAGE(PG8_SA(1, 0), a3, voffA);
;             PG8_WAIT_V(8); PG8_WAIT_L(0); PG8_BAR; PG8_MMA(1, 0, At, B0); PG8_MMA(1, 1, At, B1); PG8_BAR; PG8_SCHED;
;     ...
;                     for (int n = 0; n < 2; ++n) acc[a][b][m][n] = (f32x4){0.f, 0.f, 0.f, 0.f};
;         cur = nxt; cA = nA; cB = nB; ++ui;
;         if constexpr (ALIGN_EPI) { if (wr == 1) PG8_BAR; }
	s_add_i32 s57, s57, 1
	s_cmp_lt_u32 s57, 44
	s_cbranch_scc1 .Lp9k_A_loop
	ds_read_b128 v[194:197], v157 offset:0
	ds_read_b128 v[198:201], v157 offset:1024
	ds_read_b128 v[202:205], v157 offset:2048
	s_add_i32 m0, s60, 0x18000
	s_nop 0
	global_load_lds_dwordx4 v132, s[28:29]
	ds_read_b128 v[206:209], v157 offset:3072
	ds_read_b128 v[210:213], v157 offset:4096
	ds_read_b128 v[214:217], v157 offset:5120
	s_add_i32 m0, s60, 0x1a000
	s_nop 0
	global_load_lds_dwordx4 v136, s[28:29]
	ds_read_b128 v[218:221], v157 offset:6144
	ds_read_b128 v[222:225], v157 offset:7168
	ds_read_b128 v[166:169], v155 offset:2048
	s_add_u32 s30, s28, 0x58000
	s_addc_u32 s31, s29, 0
	s_add_i32 m0, s60, 0x19000
	s_nop 0
	global_load_lds_dwordx4 v132, s[30:31]
	ds_read_b128 v[174:177], v155 offset:3072
	ds_read_b128 v[178:181], v155 offset:16384
	ds_read_b128 v[182:185], v155 offset:17408
	s_add_i32 m0, s60, 0x1b000
	s_nop 0
	global_load_lds_dwordx4 v136, s[30:31]
	ds_read_b128 v[186:189], v155 offset:18432
	ds_read_b128 v[190:193], v155 offset:19456
	ds_read_b128 v[226:229], v157 offset:16384
	s_add_u32 s30, s28, 0x160000
	s_addc_u32 s31, s29, 0
	s_add_i32 m0, s60, 0x1c000
	s_nop 0
	global_load_lds_dwordx4 v132, s[30:31]
	ds_read_b128 v[230:233], v157 offset:17408
	ds_read_b128 v[234:237], v157 offset:18432
	ds_read_b128 v[238:241], v157 offset:19456
	s_add_i32 m0, s60, 0x1e000
	s_nop 0
	global_load_lds_dwordx4 v136, s[30:31]
	ds_read_b128 v[242:245], v157 offset:20480
	ds_read_b128 v[246:249], v157 offset:21504
	ds_read_b128 v[250:253], v157 offset:22528
	s_add_u32 s30, s28, 0x1b8000
	s_addc_u32 s31, s29, 0
	s_add_i32 m0, s60, 0x1d000
	s_nop 0
	global_load_lds_dwordx4 v132, s[30:31]
	s_add_i32 m0, s60, 0x1f000
	s_nop 0
	global_load_lds_dwordx4 v136, s[30:31]
	s_add_u32 s28, s28, 0x80
	s_addc_u32 s29, s29, 0
	s_branch .Lp9k_done
.Lp9k_B_init:
	s_setprio 1
	s_sub_u32 s28, s26, 0x57f80
	s_subb_u32 s29, s27, 0
	s_sub_u32 s58, s6, 0x58000
	s_subb_u32 s59, s7, 0
	s_cmp_eq_u32 s42, 1
	s_cbranch_scc1 .Lp9k_B_nobar
	s_barrier
.Lp9k_B_nobar:
	ds_read_b128 v[194:197], v157 offset:0
	ds_read_b128 v[198:201], v157 offset:1024
	ds_read_b128 v[202:205], v157 offset:2048
	s_add_i32 m0, s60, 0xa000
	s_nop 0
	global_load_lds_dwordx4 v134, s[28:29]
	ds_read_b128 v[206:209], v157 offset:3072
	ds_read_b128 v[210:213], v157 offset:4096
	ds_read_b128 v[214:217], v157 offset:5120
	s_add_u32 s30, s28, 0x58000
	s_addc_u32 s31, s29, 0
	s_add_i32 m0, s60, 0xb000
	s_nop 0
	global_load_lds_dwordx4 v134, s[30:31]
	ds_read_b128 v[218:221], v157 offset:6144
	ds_read_b128 v[222:225], v157 offset:7168
	ds_read_b128 v[158:161], v155 offset:0
	s_add_u32 s30, s28, 0x160000
	s_addc_u32 s31, s29, 0
	s_add_i32 m0, s60, 0xe000
	s_nop 0
	global_load_lds_dwordx4 v134, s[30:31]
	ds_read_b128 v[162:165], v155 offset:1024
	ds_read_b128 v[166:169], v155 offset:2048
	ds_read_b128 v[174:177], v155 offset:3072
	s_add_u32 s30, s28, 0x1b8000
	s_addc_u32 s31, s29, 0
	s_add_i32 m0, s60, 0xf000
	s_nop 0
	global_load_lds_dwordx4 v134, s[30:31]
	ds_read_b128 v[178:181], v155 offset:16384
	ds_read_b128 v[182:185], v155 offset:17408
	ds_read_b128 v[186:189], v155 offset:18432
	s_add_u32 s34, s28, 0x80
	s_addc_u32 s35, s29, 0
	s_cmp_eq_u32 s57, 43
	s_cselect_b32 s34, s58, s34
	s_cselect_b32 s35, s59, s35
	s_add_i32 m0, s60, 0x0
	s_nop 0
	global_load_lds_dwordx4 v130, s[34:35]
	ds_read_b128 v[190:193], v155 offset:19456
	ds_read_b128 v[226:229], v157 offset:16384
	ds_read_b128 v[230:233], v157 offset:17408
	s_add_u32 s30, s34, 0x58000
	s_addc_u32 s31, s35, 0
	s_add_i32 m0, s60, 0x1000
	s_nop 0
	global_load_lds_dwordx4 v130, s[30:31]
	ds_read_b128 v[234:237], v157 offset:18432
	ds_read_b128 v[238:241], v157 offset:19456
	ds_read_b128 v[242:245], v157 offset:20480
	s_add_u32 s30, s34, 0x160000
	s_addc_u32 s31, s35, 0
	s_add_i32 m0, s60, 0x4000
	s_nop 0
	global_load_lds_dwordx4 v130, s[30:31]
	ds_read_b128 v[246:249], v157 offset:21504
	ds_read_b128 v[250:253], v157 offset:22528
	ds_read_b128 v[142:145], v157 offset:23552
	s_add_u32 s30, s34, 0x1b8000
	s_addc_u32 s31, s35, 0
	s_add_i32 m0, s60, 0x5000
	s_nop 0
	global_load_lds_dwordx4 v130, s[30:31]
	s_add_u32 s28, s28, 0x80
	s_addc_u32 s29, s29, 0
	s_waitcnt vmcnt(8) lgkmcnt(0)
	s_barrier
	v_mfma_f32_16x16x32_bf16 v[126:129], v[158:161], v[194:197], 0
	v_mfma_f32_16x16x32_bf16 v[126:129], v[162:165], v[198:201], v[126:129]
	v_mfma_f32_16x16x32_bf16 v[122:125], v[174:177], v[198:201], 0
	v_mfma_f32_16x16x32_bf16 v[122:125], v[166:169], v[194:197], v[122:125]
	v_mfma_f32_16x16x32_bf16 v[114:117], v[178:181], v[194:197], 0
	v_mfma_f32_16x16x32_bf16 v[114:117], v[182:185], v[198:201], v[114:117]
	v_mfma_f32_16x16x32_bf16 v[106:109], v[190:193], v[198:201], 0
	v_mfma_f32_16x16x32_bf16 v[106:109], v[186:189], v[194:197], v[106:109]
	v_mfma_f32_16x16x32_bf16 v[90:93], v[186:189], v[202:205], 0
	v_mfma_f32_16x16x32_bf16 v[90:93], v[190:193], v[206:209], v[90:93]
	v_mfma_f32_16x16x32_bf16 v[98:101], v[182:185], v[206:209], 0
	v_mfma_f32_16x16x32_bf16 v[98:101], v[178:181], v[202:205], v[98:101]
	v_mfma_f32_16x16x32_bf16 v[110:113], v[166:169], v[202:205], 0
	v_mfma_f32_16x16x32_bf16 v[110:113], v[174:177], v[206:209], v[110:113]
	v_mfma_f32_16x16x32_bf16 v[118:121], v[162:165], v[206:209], 0
	v_mfma_f32_16x16x32_bf16 v[118:121], v[158:161], v[202:205], v[118:121]
	v_mfma_f32_16x16x32_bf16 v[102:105], v[158:161], v[210:213], 0
	v_mfma_f32_16x16x32_bf16 v[102:105], v[162:165], v[214:217], v[102:105]
	v_mfma_f32_16x16x32_bf16 v[94:97], v[174:177], v[214:217], 0
	v_mfma_f32_16x16x32_bf16 v[94:97], v[166:169], v[210:213], v[94:97]
	v_mfma_f32_16x16x32_bf16 v[82:85], v[178:181], v[210:213], 0
; #define PG8_STAGE(bufoff, gbase, voff) do { _Pragma("unroll") for (int _i = 0; _i < 2; ++_i) \
;         __builtin_amdgcn_global_load_lds((const unsigned*)((const char*)(gbase) + (voff)[_i]), (PG8_LAS unsigned*)(lds + (bufoff) + ldsw + _i * 8192), 16, 0, 0); } while (0)
; #define PG8_LDA(dst, b, h) do { _Pragma("unroll") for (int m = 0; m < 4; ++m) _Pragma("unroll") for (int k = 0; k < 2; ++k) dst[m][k] = *(const PG8_LAS bf16x8*)(lds + PG8_SA(b, h) + aoff + m * 2048 + k * 1024); } while (0)
; #define PG8_LDB(dst, b, h) do { _Pragma("unroll") for (int n = 0; n < 2; ++n) _Pragma("unroll") for (int k = 0; k < 2; ++k) dst[n][k] = *(const PG8_LAS bf16x8*)(lds + PG8_SB(b, h) + boff + n * 2048 + k * 1024); } while (0)
; #define PG8_MMA(ai, bj, At, Bt) do { __builtin_amdgcn_s_setprio(1); _Pragma("unroll") for (int m = 0; m < 4; ++m) _Pragma("unroll") for (int n = 0; n < 2; ++n) _Pragma("unroll") for (int k = 0; k < 2; ++k) \
;         acc[ai][bj][m][n] = __builtin_amdgcn_mfma_f32_16x16x32_bf16(Bt[n][k], At[m][k], acc[ai][bj][m][n], 0, 0, 0); __builtin_amdgcn_s_setprio(0); } while (0)
; #define PG8_WAIT_V(n) asm volatile("s_waitcnt vmcnt(" #n ")" ::: "memory")
; #define PG8_WAIT_L(n) asm volatile("s_waitcnt lgkmcnt(" #n ")" ::: "memory")
; #define PG8_BAR __builtin_amdgcn_s_barrier()
; #define PG8_SCHED __builtin_amdgcn_sched_barrier(0)
; template <class Epi, class Sched, bool ALIGN_EPI>
; __device__ __forceinline__ void gemm_phase(PG8_LAS unsigned char* lds, const Gemm g, const Sched& S, const Epi& E) {
;     ...
;             PG8_WAIT_V(8); PG8_WAIT_L(0); PG8_BAR; PG8_MMA(0, 0, At, B0); PG8_MMA(0, 1, At, B1); PG8_BAR; PG8_SCHED;
;             PG8_LDA(At, 0, 1); PG8_STAGE(PG8_SB(0, 0), b2, voffB); PG8_STAGE(PG8_SB(0, 1), b2 + hstepB, voffB); PG8_STAGE(PG8_SA(0, 0), a2, voffA);
;             PG8_WAIT_V(8); PG8_WAIT_L(0); PG8_BAR; PG8_MMA(1, 0, At, B0); PG8_MMA(1, 1, At, B1); PG8_BAR; PG8_SCHED;
;             PG8_LDB(B0, 1, 0); PG8_LDB(B1, 1, 1); PG8_SCHED; PG8_LDA(At, 1, 0); PG8_STAGE(PG8_SA(0, 1), a2 + hstepA, voffA);
;             PG8_WAIT_V(8); PG8_WAIT_L(0); PG8_BAR; PG8_MMA(0, 0, At, B0); PG8_MMA(0, 1, At, B1); PG8_BAR; PG8_SCHED;
;             PG8_LDA(At, 1, 1); PG8_STAGE(PG8_SB(1, 0), b3, voffB); PG8_STAGE(PG8_SB(1, 1), b3 + hstepB, voffB); PG8_STAGE(PG8_SA(1, 0), a3, voffA);
	v_mfma_f32_16x16x32_bf16 v[82:85], v[182:185], v[214:217], v[82:85]
	v_mfma_f32_16x16x32_bf16 v[74:77], v[190:193], v[214:217], 0
	v_mfma_f32_16x16x32_bf16 v[74:77], v[186:189], v[210:213], v[74:77]
	v_mfma_f32_16x16x32_bf16 v[66:69], v[186:189], v[218:221], 0
	v_mfma_f32_16x16x32_bf16 v[66:69], v[190:193], v[222:225], v[66:69]
	v_mfma_f32_16x16x32_bf16 v[70:73], v[182:185], v[222:225], 0
	v_mfma_f32_16x16x32_bf16 v[70:73], v[178:181], v[218:221], v[70:73]
	v_mfma_f32_16x16x32_bf16 v[78:81], v[166:169], v[218:221], 0
	v_mfma_f32_16x16x32_bf16 v[78:81], v[174:177], v[222:225], v[78:81]
	v_mfma_f32_16x16x32_bf16 v[86:89], v[162:165], v[222:225], 0
	v_mfma_f32_16x16x32_bf16 v[86:89], v[158:161], v[218:221], v[86:89]
	v_mfma_f32_16x16x32_bf16 v[62:65], v[158:161], v[226:229], 0
	v_mfma_f32_16x16x32_bf16 v[62:65], v[162:165], v[230:233], v[62:65]
	v_mfma_f32_16x16x32_bf16 v[58:61], v[174:177], v[230:233], 0
	v_mfma_f32_16x16x32_bf16 v[58:61], v[166:169], v[226:229], v[58:61]
	v_mfma_f32_16x16x32_bf16 v[50:53], v[178:181], v[226:229], 0
	v_mfma_f32_16x16x32_bf16 v[50:53], v[182:185], v[230:233], v[50:53]
	v_mfma_f32_16x16x32_bf16 v[42:45], v[190:193], v[230:233], 0
	v_mfma_f32_16x16x32_bf16 v[42:45], v[186:189], v[226:229], v[42:45]
	v_mfma_f32_16x16x32_bf16 v[26:29], v[186:189], v[234:237], 0
	v_mfma_f32_16x16x32_bf16 v[26:29], v[190:193], v[238:241], v[26:29]
	v_mfma_f32_16x16x32_bf16 v[34:37], v[182:185], v[238:241], 0
	v_mfma_f32_16x16x32_bf16 v[34:37], v[178:181], v[234:237], v[34:37]
	v_mfma_f32_16x16x32_bf16 v[46:49], v[166:169], v[234:237], 0
	v_mfma_f32_16x16x32_bf16 v[46:49], v[174:177], v[238:241], v[46:49]
	v_mfma_f32_16x16x32_bf16 v[54:57], v[162:165], v[238:241], 0
	v_mfma_f32_16x16x32_bf16 v[54:57], v[158:161], v[234:237], v[54:57]
	v_mfma_f32_16x16x32_bf16 v[38:41], v[158:161], v[242:245], 0
	v_mfma_f32_16x16x32_bf16 v[38:41], v[162:165], v[246:249], v[38:41]
	v_mfma_f32_16x16x32_bf16 v[30:33], v[174:177], v[246:249], 0
	v_mfma_f32_16x16x32_bf16 v[30:33], v[166:169], v[242:245], v[30:33]
	v_mfma_f32_16x16x32_bf16 v[18:21], v[178:181], v[242:245], 0
	v_mfma_f32_16x16x32_bf16 v[18:21], v[182:185], v[246:249], v[18:21]
	v_mfma_f32_16x16x32_bf16 v[10:13], v[190:193], v[246:249], 0
	v_mfma_f32_16x16x32_bf16 v[10:13], v[186:189], v[242:245], v[10:13]
	v_mfma_f32_16x16x32_bf16 v[2:5], v[186:189], v[250:253], 0
	v_mfma_f32_16x16x32_bf16 v[2:5], v[190:193], v[142:145], v[2:5]
	v_mfma_f32_16x16x32_bf16 v[6:9], v[182:185], v[142:145], 0
	v_mfma_f32_16x16x32_bf16 v[6:9], v[178:181], v[250:253], v[6:9]
	v_mfma_f32_16x16x32_bf16 v[14:17], v[166:169], v[250:253], 0
	v_mfma_f32_16x16x32_bf16 v[14:17], v[174:177], v[142:145], v[14:17]
	v_mfma_f32_16x16x32_bf16 v[22:25], v[162:165], v[142:145], 0
	v_mfma_f32_16x16x32_bf16 v[22:25], v[158:161], v[250:253], v[22:25]
	s_waitcnt vmcnt(0)
	s_barrier
	ds_read_b128 v[194:197], v157 offset:32768
	ds_read_b128 v[198:201], v157 offset:33792
	ds_read_b128 v[202:205], v157 offset:34816
	s_cmp_eq_u32 s57, 43
	s_cselect_b32 s28, s58, s28
	s_cselect_b32 s29, s59, s29
	s_add_i32 m0, s60, 0x2000
	s_nop 0
	global_load_lds_dwordx4 v134, s[28:29]
	ds_read_b128 v[206:209], v157 offset:35840
	ds_read_b128 v[210:213], v157 offset:36864
	ds_read_b128 v[214:217], v157 offset:37888
	s_add_u32 s30, s28, 0x58000
	s_addc_u32 s31, s29, 0
	s_add_i32 m0, s60, 0x3000
	s_nop 0
	global_load_lds_dwordx4 v134, s[30:31]
	ds_read_b128 v[218:221], v157 offset:38912
	ds_read_b128 v[222:225], v157 offset:39936
	ds_read_b128 v[158:161], v155 offset:32768
	s_add_u32 s30, s28, 0x160000
	s_addc_u32 s31, s29, 0
	s_add_i32 m0, s60, 0x6000
	s_nop 0
	global_load_lds_dwordx4 v134, s[30:31]
	ds_read_b128 v[162:165], v155 offset:33792
	ds_read_b128 v[166:169], v155 offset:34816
	ds_read_b128 v[174:177], v155 offset:35840
	s_add_u32 s30, s28, 0x1b8000
	s_addc_u32 s31, s29, 0
	s_add_i32 m0, s60, 0x7000
	s_nop 0
	global_load_lds_dwordx4 v134, s[30:31]
	ds_read_b128 v[178:181], v155 offset:49152
	ds_read_b128 v[182:185], v155 offset:50176
	ds_read_b128 v[186:189], v155 offset:51200
	s_add_u32 s34, s28, 0x80
	s_addc_u32 s35, s29, 0
	s_add_i32 m0, s60, 0x8000
	s_nop 0
	global_load_lds_dwordx4 v130, s[34:35]
	ds_read_b128 v[190:193], v155 offset:52224
	ds_read_b128 v[226:229], v157 offset:49152
	ds_read_b128 v[230:233], v157 offset:50176
	s_add_u32 s30, s34, 0x58000
	s_addc_u32 s31, s35, 0
	s_add_i32 m0, s60, 0x9000
	s_nop 0
	global_load_lds_dwordx4 v130, s[30:31]
	ds_read_b128 v[234:237], v157 offset:51200
	ds_read_b128 v[238:241], v157 offset:52224
	ds_read_b128 v[242:245], v157 offset:53248
	s_add_u32 s30, s34, 0x160000
	s_addc_u32 s31, s35, 0
	s_add_i32 m0, s60, 0xc000
	s_nop 0
	global_load_lds_dwordx4 v130, s[30:31]
	ds_read_b128 v[246:249], v157 offset:54272
	ds_read_b128 v[250:253], v157 offset:55296
	ds_read_b128 v[142:145], v157 offset:56320
	s_add_u32 s30, s34, 0x1b8000
	s_addc_u32 s31, s35, 0
	s_add_i32 m0, s60, 0xd000
	s_nop 0
	global_load_lds_dwordx4 v130, s[30:31]
	s_add_u32 s28, s28, 0x80
	s_addc_u32 s29, s29, 0
	s_waitcnt vmcnt(8) lgkmcnt(0)
	s_barrier
; #define PG8_STAGE(bufoff, gbase, voff) do { _Pragma("unroll") for (int _i = 0; _i < 2; ++_i) \
;         __builtin_amdgcn_global_load_lds((const unsigned*)((const char*)(gbase) + (voff)[_i]), (PG8_LAS unsigned*)(lds + (bufoff) + ldsw + _i * 8192), 16, 0, 0); } while (0)
; #define PG8_LDA(dst, b, h) do { _Pragma("unroll") for (int m = 0; m < 4; ++m) _Pragma("unroll") for (int k = 0; k < 2; ++k) dst[m][k] = *(const PG8_LAS bf16x8*)(lds + PG8_SA(b, h) + aoff + m * 2048 + k * 1024); } while (0)
; #define PG8_LDB(dst, b, h) do { _Pragma("unroll") for (int n = 0; n < 2; ++n) _Pragma("unroll") for (int k = 0; k < 2; ++k) dst[n][k] = *(const PG8_LAS bf16x8*)(lds + PG8_SB(b, h) + boff + n * 2048 + k * 1024); } while (0)
; #define PG8_MMA(ai, bj, At, Bt) do { __builtin_amdgcn_s_setprio(1); _Pragma("unroll") for (int m = 0; m < 4; ++m) _Pragma("unroll") for (int n = 0; n < 2; ++n) _Pragma("unroll") for (int k = 0; k < 2; ++k) \
;         acc[ai][bj][m][n] = __builtin_amdgcn_mfma_f32_16x16x32_bf16(Bt[n][k], At[m][k], acc[ai][bj][m][n], 0, 0, 0); __builtin_amdgcn_s_setprio(0); } while (0)
; #define PG8_WAIT_V(n) asm volatile("s_waitcnt vmcnt(" #n ")" ::: "memory")
; #define PG8_WAIT_L(n) asm volatile("s_waitcnt lgkmcnt(" #n ")" ::: "memory")
; #define PG8_BAR __builtin_amdgcn_s_barrier()
; #define PG8_SCHED __builtin_amdgcn_sched_barrier(0)
; template <class Epi, class Sched, bool ALIGN_EPI>
; __device__ __forceinline__ void gemm_phase(PG8_LAS unsigned char* lds, const Gemm g, const Sched& S, const Epi& E) {
;     ...
;             PG8_WAIT_V(8); PG8_WAIT_L(0); PG8_BAR; PG8_MMA(1, 0, At, B0); PG8_MMA(1, 1, At, B1); PG8_BAR; PG8_SCHED;
;             PG8_LDB(B0, 1, 0); PG8_LDB(B1, 1, 1); PG8_SCHED; PG8_LDA(At, 1, 0); PG8_STAGE(PG8_SA(0, 1), a2 + hstepA, voffA);
;             PG8_WAIT_V(8); PG8_WAIT_L(0); PG8_BAR; PG8_MMA(0, 0, At, B0); PG8_MMA(0, 1, At, B1); PG8_BAR; PG8_SCHED;
;             PG8_LDA(At, 1, 1); PG8_STAGE(PG8_SB(1, 0), b3, voffB); PG8_STAGE(PG8_SB(1, 1), b3 + hstepB, voffB); PG8_STAGE(PG8_SA(1, 0), a3, voffA);
;             PG8_WAIT_V(8); PG8_WAIT_L(0); PG8_BAR; PG8_MMA(1, 0, At, B0); PG8_MMA(1, 1, At, B1); PG8_BAR; PG8_SCHED;
;         }
	v_mfma_f32_16x16x32_bf16 v[126:129], v[158:161], v[194:197], v[126:129]
	v_mfma_f32_16x16x32_bf16 v[126:129], v[162:165], v[198:201], v[126:129]
	v_mfma_f32_16x16x32_bf16 v[122:125], v[174:177], v[198:201], v[122:125]
	v_mfma_f32_16x16x32_bf16 v[122:125], v[166:169], v[194:197], v[122:125]
	v_mfma_f32_16x16x32_bf16 v[114:117], v[178:181], v[194:197], v[114:117]
	v_mfma_f32_16x16x32_bf16 v[114:117], v[182:185], v[198:201], v[114:117]
	v_mfma_f32_16x16x32_bf16 v[106:109], v[190:193], v[198:201], v[106:109]
	v_mfma_f32_16x16x32_bf16 v[106:109], v[186:189], v[194:197], v[106:109]
	v_mfma_f32_16x16x32_bf16 v[90:93], v[186:189], v[202:205], v[90:93]
	v_mfma_f32_16x16x32_bf16 v[90:93], v[190:193], v[206:209], v[90:93]
	v_mfma_f32_16x16x32_bf16 v[98:101], v[182:185], v[206:209], v[98:101]
	v_mfma_f32_16x16x32_bf16 v[98:101], v[178:181], v[202:205], v[98:101]
	v_mfma_f32_16x16x32_bf16 v[110:113], v[166:169], v[202:205], v[110:113]
	v_mfma_f32_16x16x32_bf16 v[110:113], v[174:177], v[206:209], v[110:113]
	v_mfma_f32_16x16x32_bf16 v[118:121], v[162:165], v[206:209], v[118:121]
	v_mfma_f32_16x16x32_bf16 v[118:121], v[158:161], v[202:205], v[118:121]
	v_mfma_f32_16x16x32_bf16 v[102:105], v[158:161], v[210:213], v[102:105]
	v_mfma_f32_16x16x32_bf16 v[102:105], v[162:165], v[214:217], v[102:105]
	v_mfma_f32_16x16x32_bf16 v[94:97], v[174:177], v[214:217], v[94:97]
	v_mfma_f32_16x16x32_bf16 v[94:97], v[166:169], v[210:213], v[94:97]
	v_mfma_f32_16x16x32_bf16 v[82:85], v[178:181], v[210:213], v[82:85]
	v_mfma_f32_16x16x32_bf16 v[82:85], v[182:185], v[214:217], v[82:85]
	v_mfma_f32_16x16x32_bf16 v[74:77], v[190:193], v[214:217], v[74:77]
	v_mfma_f32_16x16x32_bf16 v[74:77], v[186:189], v[210:213], v[74:77]
	v_mfma_f32_16x16x32_bf16 v[66:69], v[186:189], v[218:221], v[66:69]
	v_mfma_f32_16x16x32_bf16 v[66:69], v[190:193], v[222:225], v[66:69]
	v_mfma_f32_16x16x32_bf16 v[70:73], v[182:185], v[222:225], v[70:73]
	v_mfma_f32_16x16x32_bf16 v[70:73], v[178:181], v[218:221], v[70:73]
	v_mfma_f32_16x16x32_bf16 v[78:81], v[166:169], v[218:221], v[78:81]
	v_mfma_f32_16x16x32_bf16 v[78:81], v[174:177], v[222:225], v[78:81]
	v_mfma_f32_16x16x32_bf16 v[86:89], v[162:165], v[222:225], v[86:89]
	v_mfma_f32_16x16x32_bf16 v[86:89], v[158:161], v[218:221], v[86:89]
	v_mfma_f32_16x16x32_bf16 v[62:65], v[158:161], v[226:229], v[62:65]
	v_mfma_f32_16x16x32_bf16 v[62:65], v[162:165], v[230:233], v[62:65]
	v_mfma_f32_16x16x32_bf16 v[58:61], v[174:177], v[230:233], v[58:61]
	v_mfma_f32_16x16x32_bf16 v[58:61], v[166:169], v[226:229], v[58:61]
	v_mfma_f32_16x16x32_bf16 v[50:53], v[178:181], v[226:229], v[50:53]
	v_mfma_f32_16x16x32_bf16 v[50:53], v[182:185], v[230:233], v[50:53]
	v_mfma_f32_16x16x32_bf16 v[42:45], v[190:193], v[230:233], v[42:45]
	v_mfma_f32_16x16x32_bf16 v[42:45], v[186:189], v[226:229], v[42:45]
	v_mfma_f32_16x16x32_bf16 v[26:29], v[186:189], v[234:237], v[26:29]
	v_mfma_f32_16x16x32_bf16 v[26:29], v[190:193], v[238:241], v[26:29]
	v_mfma_f32_16x16x32_bf16 v[34:37], v[182:185], v[238:241], v[34:37]
	v_mfma_f32_16x16x32_bf16 v[34:37], v[178:181], v[234:237], v[34:37]
	v_mfma_f32_16x16x32_bf16 v[46:49], v[166:169], v[234:237], v[46:49]
	v_mfma_f32_16x16x32_bf16 v[46:49], v[174:177], v[238:241], v[46:49]
	v_mfma_f32_16x16x32_bf16 v[54:57], v[162:165], v[238:241], v[54:57]
	v_mfma_f32_16x16x32_bf16 v[54:57], v[158:161], v[234:237], v[54:57]
	v_mfma_f32_16x16x32_bf16 v[38:41], v[158:161], v[242:245], v[38:41]
	v_mfma_f32_16x16x32_bf16 v[38:41], v[162:165], v[246:249], v[38:41]
	v_mfma_f32_16x16x32_bf16 v[30:33], v[174:177], v[246:249], v[30:33]
	v_mfma_f32_16x16x32_bf16 v[30:33], v[166:169], v[242:245], v[30:33]
	v_mfma_f32_16x16x32_bf16 v[18:21], v[178:181], v[242:245], v[18:21]
	v_mfma_f32_16x16x32_bf16 v[18:21], v[182:185], v[246:249], v[18:21]
	v_mfma_f32_16x16x32_bf16 v[10:13], v[190:193], v[246:249], v[10:13]
	v_mfma_f32_16x16x32_bf16 v[10:13], v[186:189], v[242:245], v[10:13]
	v_mfma_f32_16x16x32_bf16 v[2:5], v[186:189], v[250:253], v[2:5]
	v_mfma_f32_16x16x32_bf16 v[2:5], v[190:193], v[142:145], v[2:5]
	v_mfma_f32_16x16x32_bf16 v[6:9], v[182:185], v[142:145], v[6:9]
	v_mfma_f32_16x16x32_bf16 v[6:9], v[178:181], v[250:253], v[6:9]
	v_mfma_f32_16x16x32_bf16 v[14:17], v[166:169], v[250:253], v[14:17]
	v_mfma_f32_16x16x32_bf16 v[14:17], v[174:177], v[142:145], v[14:17]
	v_mfma_f32_16x16x32_bf16 v[22:25], v[162:165], v[142:145], v[22:25]
	v_mfma_f32_16x16x32_bf16 v[22:25], v[158:161], v[250:253], v[22:25]
	s_waitcnt vmcnt(0)
	s_barrier
	s_add_i32 s57, s57, 1
; #define PG8_STAGE(bufoff, gbase, voff) do { _Pragma("unroll") for (int _i = 0; _i < 2; ++_i) \
;         __builtin_amdgcn_global_load_lds((const unsigned*)((const char*)(gbase) + (voff)[_i]), (PG8_LAS unsigned*)(lds + (bufoff) + ldsw + _i * 8192), 16, 0, 0); } while (0)
; #define PG8_LDA(dst, b, h) do { _Pragma("unroll") for (int m = 0; m < 4; ++m) _Pragma("unroll") for (int k = 0; k < 2; ++k) dst[m][k] = *(const PG8_LAS bf16x8*)(lds + PG8_SA(b, h) + aoff + m * 2048 + k * 1024); } while (0)
; #define PG8_LDB(dst, b, h) do { _Pragma("unroll") for (int n = 0; n < 2; ++n) _Pragma("unroll") for (int k = 0; k < 2; ++k) dst[n][k] = *(const PG8_LAS bf16x8*)(lds + PG8_SB(b, h) + boff + n * 2048 + k * 1024); } while (0)
; #define PG8_MMA(ai, bj, At, Bt) do { __builtin_amdgcn_s_setprio(1); _Pragma("unroll") for (int m = 0; m < 4; ++m) _Pragma("unroll") for (int n = 0; n < 2; ++n) _Pragma("unroll") for (int k = 0; k < 2; ++k) \
;         acc[ai][bj][m][n] = __builtin_amdgcn_mfma_f32_16x16x32_bf16(Bt[n][k], At[m][k], acc[ai][bj][m][n], 0, 0, 0); __builtin_amdgcn_s_setprio(0); } while (0)
; #define PG8_WAIT_V(n) asm volatile("s_waitcnt vmcnt(" #n ")" ::: "memory")
; #define PG8_WAIT_L(n) asm volatile("s_waitcnt lgkmcnt(" #n ")" ::: "memory")
; #define PG8_BAR __builtin_amdgcn_s_barrier()
; #define PG8_SCHED __builtin_amdgcn_sched_barrier(0)
; template <class Epi, class Sched, bool ALIGN_EPI>
; __device__ __forceinline__ void gemm_phase(PG8_LAS unsigned char* lds, const Gemm g, const Sched& S, const Epi& E) {
;     ...
;             PG8_LDB(B0, 0, 0); PG8_LDB(B1, 0, 1); PG8_SCHED; PG8_LDA(At, 0, 0); PG8_STAGE(PG8_SA(1, 1), a1 + hstepA, voffA);
;             PG8_WAIT_V(8); PG8_WAIT_L(0); PG8_BAR; PG8_MMA(0, 0, At, B0); PG8_MMA(0, 1, At, B1); PG8_BAR; PG8_SCHED;
;             PG8_LDA(At, 0, 1); PG8_STAGE(PG8_SB(0, 0), b2, voffB); PG8_STAGE(PG8_SB(0, 1), b2 + hstepB, voffB); PG8_STAGE(PG8_SA(0, 0), a2, voffA);
;             PG8_WAIT_V(8); PG8_WAIT_L(0); PG8_BAR; PG8_MMA(1, 0, At, B0); PG8_MMA(1, 1, At, B1); PG8_BAR; PG8_SCHED;
;             PG8_LDB(B0, 1, 0); PG8_LDB(B1, 1, 1); PG8_SCHED; PG8_LDA(At, 1, 0); PG8_STAGE(PG8_SA(0, 1), a2 + hstepA, voffA);
;             PG8_WAIT_V(8); PG8_WAIT_L(0); PG8_BAR; PG8_MMA(0, 0, At, B0); PG8_MMA(0, 1, At, B1); PG8_BAR; PG8_SCHED;
.Lp9k_B_loop:
	ds_read_b128 v[194:197], v157 offset:0
	ds_read_b128 v[198:201], v157 offset:1024
	ds_read_b128 v[202:205], v157 offset:2048
	s_add_i32 m0, s60, 0xa000
	s_nop 0
	global_load_lds_dwordx4 v134, s[28:29]
	ds_read_b128 v[206:209], v157 offset:3072
	ds_read_b128 v[210:213], v157 offset:4096
	ds_read_b128 v[214:217], v157 offset:5120
	s_add_u32 s30, s28, 0x58000
	s_addc_u32 s31, s29, 0
	s_add_i32 m0, s60, 0xb000
	s_nop 0
	global_load_lds_dwordx4 v134, s[30:31]
	ds_read_b128 v[218:221], v157 offset:6144
	ds_read_b128 v[222:225], v157 offset:7168
	ds_read_b128 v[158:161], v155 offset:0
	s_add_u32 s30, s28, 0x160000
	s_addc_u32 s31, s29, 0
	s_add_i32 m0, s60, 0xe000
	s_nop 0
	global_load_lds_dwordx4 v134, s[30:31]
	ds_read_b128 v[162:165], v155 offset:1024
	ds_read_b128 v[166:169], v155 offset:2048
	ds_read_b128 v[174:177], v155 offset:3072
	s_add_u32 s30, s28, 0x1b8000
	s_addc_u32 s31, s29, 0
	s_add_i32 m0, s60, 0xf000
	s_nop 0
	global_load_lds_dwordx4 v134, s[30:31]
	ds_read_b128 v[178:181], v155 offset:16384
	ds_read_b128 v[182:185], v155 offset:17408
	ds_read_b128 v[186:189], v155 offset:18432
	s_add_u32 s34, s28, 0x80
	s_addc_u32 s35, s29, 0
	s_cmp_eq_u32 s57, 43
	s_cselect_b32 s34, s58, s34
	s_cselect_b32 s35, s59, s35
	s_add_i32 m0, s60, 0x0
	s_nop 0
	global_load_lds_dwordx4 v130, s[34:35]
	ds_read_b128 v[190:193], v155 offset:19456
	ds_read_b128 v[226:229], v157 offset:16384
	ds_read_b128 v[230:233], v157 offset:17408
	s_add_u32 s30, s34, 0x58000
	s_addc_u32 s31, s35, 0
	s_add_i32 m0, s60, 0x1000
	s_nop 0
	global_load_lds_dwordx4 v130, s[30:31]
	ds_read_b128 v[234:237], v157 offset:18432
	ds_read_b128 v[238:241], v157 offset:19456
	ds_read_b128 v[242:245], v157 offset:20480
	s_add_u32 s30, s34, 0x160000
	s_addc_u32 s31, s35, 0
	s_add_i32 m0, s60, 0x4000
	s_nop 0
	global_load_lds_dwordx4 v130, s[30:31]
	ds_read_b128 v[246:249], v157 offset:21504
	ds_read_b128 v[250:253], v157 offset:22528
	ds_read_b128 v[142:145], v157 offset:23552
	s_add_u32 s30, s34, 0x1b8000
	s_addc_u32 s31, s35, 0
	s_add_i32 m0, s60, 0x5000
	s_nop 0
	global_load_lds_dwordx4 v130, s[30:31]
	s_add_u32 s28, s28, 0x80
	s_addc_u32 s29, s29, 0
	s_waitcnt vmcnt(8) lgkmcnt(0)
	s_barrier
	v_mfma_f32_16x16x32_bf16 v[126:129], v[158:161], v[194:197], v[126:129]
	v_mfma_f32_16x16x32_bf16 v[126:129], v[162:165], v[198:201], v[126:129]
	v_mfma_f32_16x16x32_bf16 v[122:125], v[174:177], v[198:201], v[122:125]
	v_mfma_f32_16x16x32_bf16 v[122:125], v[166:169], v[194:197], v[122:125]
	v_mfma_f32_16x16x32_bf16 v[114:117], v[178:181], v[194:197], v[114:117]
	v_mfma_f32_16x16x32_bf16 v[114:117], v[182:185], v[198:201], v[114:117]
	v_mfma_f32_16x16x32_bf16 v[106:109], v[190:193], v[198:201], v[106:109]
	v_mfma_f32_16x16x32_bf16 v[106:109], v[186:189], v[194:197], v[106:109]
	v_mfma_f32_16x16x32_bf16 v[90:93], v[186:189], v[202:205], v[90:93]
	v_mfma_f32_16x16x32_bf16 v[90:93], v[190:193], v[206:209], v[90:93]
	v_mfma_f32_16x16x32_bf16 v[98:101], v[182:185], v[206:209], v[98:101]
	v_mfma_f32_16x16x32_bf16 v[98:101], v[178:181], v[202:205], v[98:101]
	v_mfma_f32_16x16x32_bf16 v[110:113], v[166:169], v[202:205], v[110:113]
	v_mfma_f32_16x16x32_bf16 v[110:113], v[174:177], v[206:209], v[110:113]
	v_mfma_f32_16x16x32_bf16 v[118:121], v[162:165], v[206:209], v[118:121]
	v_mfma_f32_16x16x32_bf16 v[118:121], v[158:161], v[202:205], v[118:121]
	v_mfma_f32_16x16x32_bf16 v[102:105], v[158:161], v[210:213], v[102:105]
	v_mfma_f32_16x16x32_bf16 v[102:105], v[162:165], v[214:217], v[102:105]
	v_mfma_f32_16x16x32_bf16 v[94:97], v[174:177], v[214:217], v[94:97]
	v_mfma_f32_16x16x32_bf16 v[94:97], v[166:169], v[210:213], v[94:97]
	v_mfma_f32_16x16x32_bf16 v[82:85], v[178:181], v[210:213], v[82:85]
	v_mfma_f32_16x16x32_bf16 v[82:85], v[182:185], v[214:217], v[82:85]
	v_mfma_f32_16x16x32_bf16 v[74:77], v[190:193], v[214:217], v[74:77]
	v_mfma_f32_16x16x32_bf16 v[74:77], v[186:189], v[210:213], v[74:77]
	v_mfma_f32_16x16x32_bf16 v[66:69], v[186:189], v[218:221], v[66:69]
	v_mfma_f32_16x16x32_bf16 v[66:69], v[190:193], v[222:225], v[66:69]
	v_mfma_f32_16x16x32_bf16 v[70:73], v[182:185], v[222:225], v[70:73]
	v_mfma_f32_16x16x32_bf16 v[70:73], v[178:181], v[218:221], v[70:73]
	v_mfma_f32_16x16x32_bf16 v[78:81], v[166:169], v[218:221], v[78:81]
	v_mfma_f32_16x16x32_bf16 v[78:81], v[174:177], v[222:225], v[78:81]
	v_mfma_f32_16x16x32_bf16 v[86:89], v[162:165], v[222:225], v[86:89]
	v_mfma_f32_16x16x32_bf16 v[86:89], v[158:161], v[218:221], v[86:89]
	v_mfma_f32_16x16x32_bf16 v[62:65], v[158:161], v[226:229], v[62:65]
	v_mfma_f32_16x16x32_bf16 v[62:65], v[162:165], v[230:233], v[62:65]
	v_mfma_f32_16x16x32_bf16 v[58:61], v[174:177], v[230:233], v[58:61]
	v_mfma_f32_16x16x32_bf16 v[58:61], v[166:169], v[226:229], v[58:61]
	v_mfma_f32_16x16x32_bf16 v[50:53], v[178:181], v[226:229], v[50:53]
	v_mfma_f32_16x16x32_bf16 v[50:53], v[182:185], v[230:233], v[50:53]
	v_mfma_f32_16x16x32_bf16 v[42:45], v[190:193], v[230:233], v[42:45]
	v_mfma_f32_16x16x32_bf16 v[42:45], v[186:189], v[226:229], v[42:45]
	v_mfma_f32_16x16x32_bf16 v[26:29], v[186:189], v[234:237], v[26:29]
	v_mfma_f32_16x16x32_bf16 v[26:29], v[190:193], v[238:241], v[26:29]
	v_mfma_f32_16x16x32_bf16 v[34:37], v[182:185], v[238:241], v[34:37]
	v_mfma_f32_16x16x32_bf16 v[34:37], v[178:181], v[234:237], v[34:37]
	v_mfma_f32_16x16x32_bf16 v[46:49], v[166:169], v[234:237], v[46:49]
	v_mfma_f32_16x16x32_bf16 v[46:49], v[174:177], v[238:241], v[46:49]
	v_mfma_f32_16x16x32_bf16 v[54:57], v[162:165], v[238:241], v[54:57]
	v_mfma_f32_16x16x32_bf16 v[54:57], v[158:161], v[234:237], v[54:57]
	v_mfma_f32_16x16x32_bf16 v[38:41], v[158:161], v[242:245], v[38:41]
	v_mfma_f32_16x16x32_bf16 v[38:41], v[162:165], v[246:249], v[38:41]
	v_mfma_f32_16x16x32_bf16 v[30:33], v[174:177], v[246:249], v[30:33]
	v_mfma_f32_16x16x32_bf16 v[30:33], v[166:169], v[242:245], v[30:33]
	v_mfma_f32_16x16x32_bf16 v[18:21], v[178:181], v[242:245], v[18:21]
	v_mfma_f32_16x16x32_bf16 v[18:21], v[182:185], v[246:249], v[18:21]
	v_mfma_f32_16x16x32_bf16 v[10:13], v[190:193], v[246:249], v[10:13]
	v_mfma_f32_16x16x32_bf16 v[10:13], v[186:189], v[242:245], v[10:13]
	v_mfma_f32_16x16x32_bf16 v[2:5], v[186:189], v[250:253], v[2:5]
	v_mfma_f32_16x16x32_bf16 v[2:5], v[190:193], v[142:145], v[2:5]
	v_mfma_f32_16x16x32_bf16 v[6:9], v[182:185], v[142:145], v[6:9]
	v_mfma_f32_16x16x32_bf16 v[6:9], v[178:181], v[250:253], v[6:9]
	v_mfma_f32_16x16x32_bf16 v[14:17], v[166:169], v[250:253], v[14:17]
	v_mfma_f32_16x16x32_bf16 v[14:17], v[174:177], v[142:145], v[14:17]
	v_mfma_f32_16x16x32_bf16 v[22:25], v[162:165], v[142:145], v[22:25]
	v_mfma_f32_16x16x32_bf16 v[22:25], v[158:161], v[250:253], v[22:25]
	s_waitcnt vmcnt(0)
	s_barrier
; #define PG8_STAGE(bufoff, gbase, voff) do { _Pragma("unroll") for (int _i = 0; _i < 2; ++_i) \
;         __builtin_amdgcn_global_load_lds((const unsigned*)((const char*)(gbase) + (voff)[_i]), (PG8_LAS unsigned*)(lds + (bufoff) + ldsw + _i * 8192), 16, 0, 0); } while (0)
; #define PG8_LDA(dst, b, h) do { _Pragma("unroll") for (int m = 0; m < 4; ++m) _Pragma("unroll") for (int k = 0; k < 2; ++k) dst[m][k] = *(const PG8_LAS bf16x8*)(lds + PG8_SA(b, h) + aoff + m * 2048 + k * 1024); } while (0)
; #define PG8_LDB(dst, b, h) do { _Pragma("unroll") for (int n = 0; n < 2; ++n) _Pragma("unroll") for (int k = 0; k < 2; ++k) dst[n][k] = *(const PG8_LAS bf16x8*)(lds + PG8_SB(b, h) + boff + n * 2048 + k * 1024); } while (0)
; #define PG8_MMA(ai, bj, At, Bt) do { __builtin_amdgcn_s_setprio(1); _Pragma("unroll") for (int m = 0; m < 4; ++m) _Pragma("unroll") for (int n = 0; n < 2; ++n) _Pragma("unroll") for (int k = 0; k < 2; ++k) \
;         acc[ai][bj][m][n] = __builtin_amdgcn_mfma_f32_16x16x32_bf16(Bt[n][k], At[m][k], acc[ai][bj][m][n], 0, 0, 0); __builtin_amdgcn_s_setprio(0); } while (0)
; #define PG8_WAIT_V(n) asm volatile("s_waitcnt vmcnt(" #n ")" ::: "memory")
; #define PG8_WAIT_L(n) asm volatile("s_waitcnt lgkmcnt(" #n ")" ::: "memory")
; #define PG8_BAR __builtin_amdgcn_s_barrier()
; #define PG8_SCHED __builtin_amdgcn_sched_barrier(0)
; template <class Epi, class Sched, bool ALIGN_EPI>
; __device__ __forceinline__ void gemm_phase(PG8_LAS unsigned char* lds, const Gemm g, const Sched& S, const Epi& E) {
;     ...
;             PG8_LDB(B0, 1, 0); PG8_LDB(B1, 1, 1); PG8_SCHED; PG8_LDA(At, 1, 0); PG8_STAGE(PG8_SA(0, 1), a2 + hstepA, voffA);
;             PG8_WAIT_V(8); PG8_WAIT_L(0); PG8_BAR; PG8_MMA(0, 0, At, B0); PG8_MMA(0, 1, At, B1); PG8_BAR; PG8_SCHED;
;             PG8_LDA(At, 1, 1); PG8_STAGE(PG8_SB(1, 0), b3, voffB); PG8_STAGE(PG8_SB(1, 1), b3 + hstepB, voffB); PG8_STAGE(PG8_SA(1, 0), a3, voffA);
;             PG8_WAIT_V(8); PG8_WAIT_L(0); PG8_BAR; PG8_MMA(1, 0, At, B0); PG8_MMA(1, 1, At, B1); PG8_BAR; PG8_SCHED;
;         }
	ds_read_b128 v[194:197], v157 offset:32768
	ds_read_b128 v[198:201], v157 offset:33792
	ds_read_b128 v[202:205], v157 offset:34816
	s_cmp_eq_u32 s57, 43
	s_cselect_b32 s28, s58, s28
	s_cselect_b32 s29, s59, s29
	s_add_i32 m0, s60, 0x2000
	s_nop 0
	global_load_lds_dwordx4 v134, s[28:29]
	ds_read_b128 v[206:209], v157 offset:35840
	ds_read_b128 v[210:213], v157 offset:36864
	ds_read_b128 v[214:217], v157 offset:37888
	s_add_u32 s30, s28, 0x58000
	s_addc_u32 s31, s29, 0
	s_add_i32 m0, s60, 0x3000
	s_nop 0
	global_load_lds_dwordx4 v134, s[30:31]
	ds_read_b128 v[218:221], v157 offset:38912
	ds_read_b128 v[222:225], v157 offset:39936
	ds_read_b128 v[158:161], v155 offset:32768
	s_add_u32 s30, s28, 0x160000
	s_addc_u32 s31, s29, 0
	s_add_i32 m0, s60, 0x6000
	s_nop 0
	global_load_lds_dwordx4 v134, s[30:31]
	ds_read_b128 v[162:165], v155 offset:33792
	ds_read_b128 v[166:169], v155 offset:34816
	ds_read_b128 v[174:177], v155 offset:35840
	s_add_u32 s30, s28, 0x1b8000
	s_addc_u32 s31, s29, 0
	s_add_i32 m0, s60, 0x7000
	s_nop 0
	global_load_lds_dwordx4 v134, s[30:31]
	ds_read_b128 v[178:181], v155 offset:49152
	ds_read_b128 v[182:185], v155 offset:50176
	ds_read_b128 v[186:189], v155 offset:51200
	s_add_u32 s34, s28, 0x80
	s_addc_u32 s35, s29, 0
	s_add_i32 m0, s60, 0x8000
	s_nop 0
	global_load_lds_dwordx4 v130, s[34:35]
	ds_read_b128 v[190:193], v155 offset:52224
	ds_read_b128 v[226:229], v157 offset:49152
	ds_read_b128 v[230:233], v157 offset:50176
	s_add_u32 s30, s34, 0x58000
	s_addc_u32 s31, s35, 0
	s_add_i32 m0, s60, 0x9000
	s_nop 0
	global_load_lds_dwordx4 v130, s[30:31]
	ds_read_b128 v[234:237], v157 offset:51200
	ds_read_b128 v[238:241], v157 offset:52224
	ds_read_b128 v[242:245], v157 offset:53248
	s_add_u32 s30, s34, 0x160000
	s_addc_u32 s31, s35, 0
	s_add_i32 m0, s60, 0xc000
	s_nop 0
	global_load_lds_dwordx4 v130, s[30:31]
	ds_read_b128 v[246:249], v157 offset:54272
	ds_read_b128 v[250:253], v157 offset:55296
	ds_read_b128 v[142:145], v157 offset:56320
	s_add_u32 s30, s34, 0x1b8000
	s_addc_u32 s31, s35, 0
	s_add_i32 m0, s60, 0xd000
	s_nop 0
	global_load_lds_dwordx4 v130, s[30:31]
	s_add_u32 s28, s28, 0x80
	s_addc_u32 s29, s29, 0
	s_waitcnt vmcnt(8) lgkmcnt(0)
	s_barrier
	v_mfma_f32_16x16x32_bf16 v[126:129], v[158:161], v[194:197], v[126:129]
	v_mfma_f32_16x16x32_bf16 v[126:129], v[162:165], v[198:201], v[126:129]
	v_mfma_f32_16x16x32_bf16 v[122:125], v[174:177], v[198:201], v[122:125]
	v_mfma_f32_16x16x32_bf16 v[122:125], v[166:169], v[194:197], v[122:125]
	v_mfma_f32_16x16x32_bf16 v[114:117], v[178:181], v[194:197], v[114:117]
	v_mfma_f32_16x16x32_bf16 v[114:117], v[182:185], v[198:201], v[114:117]
	v_mfma_f32_16x16x32_bf16 v[106:109], v[190:193], v[198:201], v[106:109]
	v_mfma_f32_16x16x32_bf16 v[106:109], v[186:189], v[194:197], v[106:109]
	v_mfma_f32_16x16x32_bf16 v[90:93], v[186:189], v[202:205], v[90:93]
	v_mfma_f32_16x16x32_bf16 v[90:93], v[190:193], v[206:209], v[90:93]
	v_mfma_f32_16x16x32_bf16 v[98:101], v[182:185], v[206:209], v[98:101]
	v_mfma_f32_16x16x32_bf16 v[98:101], v[178:181], v[202:205], v[98:101]
	v_mfma_f32_16x16x32_bf16 v[110:113], v[166:169], v[202:205], v[110:113]
	v_mfma_f32_16x16x32_bf16 v[110:113], v[174:177], v[206:209], v[110:113]
	v_mfma_f32_16x16x32_bf16 v[118:121], v[162:165], v[206:209], v[118:121]
	v_mfma_f32_16x16x32_bf16 v[118:121], v[158:161], v[202:205], v[118:121]
	v_mfma_f32_16x16x32_bf16 v[102:105], v[158:161], v[210:213], v[102:105]
	v_mfma_f32_16x16x32_bf16 v[102:105], v[162:165], v[214:217], v[102:105]
	v_mfma_f32_16x16x32_bf16 v[94:97], v[174:177], v[214:217], v[94:97]
	v_mfma_f32_16x16x32_bf16 v[94:97], v[166:169], v[210:213], v[94:97]
	v_mfma_f32_16x16x32_bf16 v[82:85], v[178:181], v[210:213], v[82:85]
	v_mfma_f32_16x16x32_bf16 v[82:85], v[182:185], v[214:217], v[82:85]
	v_mfma_f32_16x16x32_bf16 v[74:77], v[190:193], v[214:217], v[74:77]
	v_mfma_f32_16x16x32_bf16 v[74:77], v[186:189], v[210:213], v[74:77]
	v_mfma_f32_16x16x32_bf16 v[66:69], v[186:189], v[218:221], v[66:69]
	v_mfma_f32_16x16x32_bf16 v[66:69], v[190:193], v[222:225], v[66:69]
	v_mfma_f32_16x16x32_bf16 v[70:73], v[182:185], v[222:225], v[70:73]
	v_mfma_f32_16x16x32_bf16 v[70:73], v[178:181], v[218:221], v[70:73]
	v_mfma_f32_16x16x32_bf16 v[78:81], v[166:169], v[218:221], v[78:81]
	v_mfma_f32_16x16x32_bf16 v[78:81], v[174:177], v[222:225], v[78:81]
	v_mfma_f32_16x16x32_bf16 v[86:89], v[162:165], v[222:225], v[86:89]
	v_mfma_f32_16x16x32_bf16 v[86:89], v[158:161], v[218:221], v[86:89]
	v_mfma_f32_16x16x32_bf16 v[62:65], v[158:161], v[226:229], v[62:65]
	v_mfma_f32_16x16x32_bf16 v[62:65], v[162:165], v[230:233], v[62:65]
	v_mfma_f32_16x16x32_bf16 v[58:61], v[174:177], v[230:233], v[58:61]
	v_mfma_f32_16x16x32_bf16 v[58:61], v[166:169], v[226:229], v[58:61]
	v_mfma_f32_16x16x32_bf16 v[50:53], v[178:181], v[226:229], v[50:53]
	v_mfma_f32_16x16x32_bf16 v[50:53], v[182:185], v[230:233], v[50:53]
	v_mfma_f32_16x16x32_bf16 v[42:45], v[190:193], v[230:233], v[42:45]
	v_mfma_f32_16x16x32_bf16 v[42:45], v[186:189], v[226:229], v[42:45]
	v_mfma_f32_16x16x32_bf16 v[26:29], v[186:189], v[234:237], v[26:29]
	v_mfma_f32_16x16x32_bf16 v[26:29], v[190:193], v[238:241], v[26:29]
	v_mfma_f32_16x16x32_bf16 v[34:37], v[182:185], v[238:241], v[34:37]
	v_mfma_f32_16x16x32_bf16 v[34:37], v[178:181], v[234:237], v[34:37]
	v_mfma_f32_16x16x32_bf16 v[46:49], v[166:169], v[234:237], v[46:49]
	v_mfma_f32_16x16x32_bf16 v[46:49], v[174:177], v[238:241], v[46:49]
	v_mfma_f32_16x16x32_bf16 v[54:57], v[162:165], v[238:241], v[54:57]
	v_mfma_f32_16x16x32_bf16 v[54:57], v[158:161], v[234:237], v[54:57]
	v_mfma_f32_16x16x32_bf16 v[38:41], v[158:161], v[242:245], v[38:41]
	v_mfma_f32_16x16x32_bf16 v[38:41], v[162:165], v[246:249], v[38:41]
	v_mfma_f32_16x16x32_bf16 v[30:33], v[174:177], v[246:249], v[30:33]
	v_mfma_f32_16x16x32_bf16 v[30:33], v[166:169], v[242:245], v[30:33]
	v_mfma_f32_16x16x32_bf16 v[18:21], v[178:181], v[242:245], v[18:21]
	v_mfma_f32_16x16x32_bf16 v[18:21], v[182:185], v[246:249], v[18:21]
	v_mfma_f32_16x16x32_bf16 v[10:13], v[190:193], v[246:249], v[10:13]
	v_mfma_f32_16x16x32_bf16 v[10:13], v[186:189], v[242:245], v[10:13]
	v_mfma_f32_16x16x32_bf16 v[2:5], v[186:189], v[250:253], v[2:5]
	v_mfma_f32_16x16x32_bf16 v[2:5], v[190:193], v[142:145], v[2:5]
	v_mfma_f32_16x16x32_bf16 v[6:9], v[182:185], v[142:145], v[6:9]
	v_mfma_f32_16x16x32_bf16 v[6:9], v[178:181], v[250:253], v[6:9]
	v_mfma_f32_16x16x32_bf16 v[14:17], v[166:169], v[250:253], v[14:17]
	v_mfma_f32_16x16x32_bf16 v[14:17], v[174:177], v[142:145], v[14:17]
	v_mfma_f32_16x16x32_bf16 v[22:25], v[162:165], v[142:145], v[22:25]
	v_mfma_f32_16x16x32_bf16 v[22:25], v[158:161], v[250:253], v[22:25]
	s_waitcnt vmcnt(0)
	s_add_i32 s57, s57, 1
	s_cmp_lt_u32 s57, 44
	s_cbranch_scc0 .Lp9k_B_exit
	s_barrier
	s_branch .Lp9k_B_loop
; __device__ __forceinline__ unsigned cvt_pk_bf16(float lo, float hi) { unsigned r; asm volatile("v_cvt_pk_bf16_f32 %0, %1, %2" : "=v"(r) : "v"(lo), "v"(hi)); return r; }
; #define PG8_BAR __builtin_amdgcn_s_barrier()
;     __device__ __forceinline__ void operator()(const f32x4 (&acc)[2][2][4][2], const Unit& u, int wr, int wc, int fr, int fq) const {
;         const int row0 = u.pm * BM + wr * 64 + fr, col0 = u.pn * BM + wc * 32 + 8 * fq;
; #pragma unroll
;         for (int ai = 0; ai < 2; ++ai)
; #pragma unroll
;             for (int m = 0; m < 4; ++m) { bf16_t* rowp = O + (size_t)(row0 + ai * HALF + m * 16) * ldc + col0;
; #pragma unroll
;                 for (int bj = 0; bj < 2; ++bj) { const f32x4 v0 = acc[ai][bj][m][0], v1 = acc[ai][bj][m][1];
;                     u32x4 w; w.x = cvt_pk_bf16(v0[0], v0[1]); w.y = cvt_pk_bf16(v0[2], v0[3]); w.z = cvt_pk_bf16(v1[0], v1[1]); w.w = cvt_pk_bf16(v1[2], v1[3]);
;                     *(u32x4*)(rowp + bj * HALF) = w; } }
;     }
; template <class Epi, class Sched, bool ALIGN_EPI>
; __device__ __forceinline__ void gemm_phase(PG8_LAS unsigned char* lds, const Gemm g, const Sched& S, const Epi& E) {
;     ...
;         if constexpr (ALIGN_EPI) { if (wr == 0) PG8_BAR; }
;         E(acc, cur, wr, wc, fr, fq);
;         if (!has_next) break;
.Lp9k_B_exit:
.Lp9k_done:
	v_mov_b64_e32 v[142:143], 0x200
	v_mov_b64_e32 v[144:145], 0x1ff
.LBB0_951:
	v_lshl_add_u32 v158, s55, 8, v1
	v_lshl_or_b32 v146, s56, 8, v154
	v_ashrrev_i32_e32 v159, 31, v158
	v_ashrrev_i32_e32 v147, 31, v146
	v_lshlrev_b64 v[160:161], 12, v[158:159]
	v_lshl_add_u64 v[160:161], s[84:85], 0, v[160:161]
	v_lshlrev_b64 v[162:163], 1, v[146:147]
	v_lshl_add_u64 v[146:147], v[160:161], 0, v[162:163]
	v_cvt_pk_bf16_f32 v126, v126, v127
	v_cvt_pk_bf16_f32 v127, v128, v129
	v_cvt_pk_bf16_f32 v128, v122, v123
	v_cvt_pk_bf16_f32 v129, v124, v125
	global_store_dwordx4 v[146:147], v[126:129], off
	v_cvt_pk_bf16_f32 v114, v114, v115
	v_cvt_pk_bf16_f32 v115, v116, v117
	v_cvt_pk_bf16_f32 v116, v106, v107
	v_or_b32_e32 v106, 16, v158
	v_ashrrev_i32_e32 v107, 31, v106
	v_lshlrev_b64 v[106:107], 12, v[106:107]
	v_lshl_add_u64 v[106:107], s[84:85], 0, v[106:107]
	v_cvt_pk_bf16_f32 v117, v108, v109
	global_store_dwordx4 v[146:147], v[114:117], off offset:256
	s_nop 1
	v_lshl_add_u64 v[114:115], v[106:107], 0, v[162:163]
	v_cvt_pk_bf16_f32 v106, v118, v119
	v_cvt_pk_bf16_f32 v107, v120, v121
	v_cvt_pk_bf16_f32 v108, v110, v111
	v_cvt_pk_bf16_f32 v109, v112, v113
	global_store_dwordx4 v[114:115], v[106:109], off
	v_cvt_pk_bf16_f32 v98, v98, v99
	v_cvt_pk_bf16_f32 v99, v100, v101
	v_cvt_pk_bf16_f32 v100, v90, v91
	v_or_b32_e32 v90, 32, v158
	v_ashrrev_i32_e32 v91, 31, v90
	v_lshlrev_b64 v[90:91], 12, v[90:91]
	v_lshl_add_u64 v[90:91], s[84:85], 0, v[90:91]
	v_cvt_pk_bf16_f32 v101, v92, v93
	global_store_dwordx4 v[114:115], v[98:101], off offset:256
	s_nop 1
	v_lshl_add_u64 v[98:99], v[90:91], 0, v[162:163]
	v_cvt_pk_bf16_f32 v90, v102, v103
	v_cvt_pk_bf16_f32 v91, v104, v105
	v_cvt_pk_bf16_f32 v92, v94, v95
	v_cvt_pk_bf16_f32 v93, v96, v97
	global_store_dwordx4 v[98:99], v[90:93], off
	v_cvt_pk_bf16_f32 v82, v82, v83
	v_cvt_pk_bf16_f32 v83, v84, v85
	v_cvt_pk_bf16_f32 v84, v74, v75
	v_or_b32_e32 v74, 48, v158
	v_ashrrev_i32_e32 v75, 31, v74
	v_lshlrev_b64 v[74:75], 12, v[74:75]
	v_lshl_add_u64 v[74:75], s[84:85], 0, v[74:75]
	v_cvt_pk_bf16_f32 v85, v76, v77
	global_store_dwordx4 v[98:99], v[82:85], off offset:256
	s_nop 1
	v_lshl_add_u64 v[82:83], v[74:75], 0, v[162:163]
	v_cvt_pk_bf16_f32 v74, v86, v87
	v_cvt_pk_bf16_f32 v75, v88, v89
	v_cvt_pk_bf16_f32 v76, v78, v79
	v_cvt_pk_bf16_f32 v77, v80, v81
	global_store_dwordx4 v[82:83], v[74:77], off
	v_cvt_pk_bf16_f32 v70, v70, v71
	v_cvt_pk_bf16_f32 v71, v72, v73
	v_cvt_pk_bf16_f32 v72, v66, v67
	v_cvt_pk_bf16_f32 v73, v68, v69
	global_store_dwordx4 v[82:83], v[70:73], off offset:256
	v_cvt_pk_bf16_f32 v62, v62, v63
	v_cvt_pk_bf16_f32 v63, v64, v65
	v_cvt_pk_bf16_f32 v64, v58, v59
	v_add_co_u32_e32 v58, vcc, s49, v146
	v_lshl_add_u64 v[66:67], v[146:147], 0, s[16:17]
	s_nop 0
	v_addc_co_u32_e32 v59, vcc, 0, v147, vcc
	v_cvt_pk_bf16_f32 v65, v60, v61
	global_store_dwordx4 v[58:59], v[62:65], off
	v_cvt_pk_bf16_f32 v50, v50, v51
	v_cvt_pk_bf16_f32 v51, v52, v53
	v_cvt_pk_bf16_f32 v52, v42, v43
	v_cvt_pk_bf16_f32 v53, v44, v45
	global_store_dwordx4 v[66:67], v[50:53], off offset:256
	v_cvt_pk_bf16_f32 v42, v54, v55
	v_cvt_pk_bf16_f32 v43, v56, v57
	v_cvt_pk_bf16_f32 v44, v46, v47
	v_add_co_u32_e32 v46, vcc, s50, v146
	s_nop 0
	v_lshl_add_u64 v[50:51], v[146:147], 0, s[18:19]
	v_addc_co_u32_e32 v47, vcc, 0, v147, vcc
	v_cvt_pk_bf16_f32 v45, v48, v49
	global_store_dwordx4 v[46:47], v[42:45], off
	v_cvt_pk_bf16_f32 v34, v34, v35
	v_cvt_pk_bf16_f32 v35, v36, v37
	v_cvt_pk_bf16_f32 v36, v26, v27
	v_cvt_pk_bf16_f32 v37, v28, v29
	global_store_dwordx4 v[50:51], v[34:37], off offset:256
	v_cvt_pk_bf16_f32 v26, v38, v39
	v_cvt_pk_bf16_f32 v27, v40, v41
	v_cvt_pk_bf16_f32 v28, v30, v31
	v_add_co_u32_e32 v30, vcc, s51, v146
	s_nop 0
	v_lshl_add_u64 v[34:35], v[146:147], 0, s[20:21]
	v_addc_co_u32_e32 v31, vcc, 0, v147, vcc
	v_cvt_pk_bf16_f32 v29, v32, v33
	global_store_dwordx4 v[30:31], v[26:29], off
	v_cvt_pk_bf16_f32 v18, v18, v19
	v_cvt_pk_bf16_f32 v19, v20, v21
	v_cvt_pk_bf16_f32 v20, v10, v11
	v_cvt_pk_bf16_f32 v21, v12, v13
	global_store_dwordx4 v[34:35], v[18:21], off offset:256
	v_cvt_pk_bf16_f32 v10, v22, v23
	v_cvt_pk_bf16_f32 v11, v24, v25
	v_cvt_pk_bf16_f32 v12, v14, v15
	v_add_co_u32_e32 v14, vcc, s52, v146
	s_nop 0
	v_lshl_add_u64 v[18:19], v[146:147], 0, s[22:23]
	v_addc_co_u32_e32 v15, vcc, 0, v147, vcc
	s_and_b64 vcc, exec, s[0:1]
	s_mov_b64 s[0:1], -1
	v_cvt_pk_bf16_f32 v13, v16, v17
	global_store_dwordx4 v[14:15], v[10:13], off
	v_cvt_pk_bf16_f32 v6, v6, v7
	v_cvt_pk_bf16_f32 v7, v8, v9
	v_cvt_pk_bf16_f32 v8, v2, v3
	v_cvt_pk_bf16_f32 v9, v4, v5
	global_store_dwordx4 v[18:19], v[6:9], off offset:256
	s_cbranch_vccnz .LBB0_936
	s_branch .LBB0_935
